# K-loop LDS second-buffer read bases kept in two spare VGPRs (load segments VALU-free) + dtype comment
# baseline (speedup 1.0000x reference)
.LBB0_258:
	s_lshl_b32 s3, s3, 5
	s_mov_b64 s[34:35], 0x80
	s_and_b32 s3, s3, 0x60
	s_add_i32 m0, s31, 0x18000
	v_lshl_add_u64 v[6:7], v[6:7], 0, s[34:35]
	s_lshl_b32 s6, s1, 13
	s_lshl_b32 s7, s3, 7
	s_waitcnt vmcnt(2)
	s_barrier
	global_load_lds_dwordx4 v[6:7], off
	v_lshl_add_u64 v[4:5], v[4:5], 0, s[34:35]
	s_add_i32 m0, s31, 0x1a000
	s_add_i32 s73, s31, 0x8000
	s_add_i32 s80, s31, 0xa000
	global_load_lds_dwordx4 v[4:5], off
	v_lshl_add_u64 v[0:1], v[0:1], 0, s[34:35]
	s_mov_b32 m0, s73
	s_add_u32 s4, s76, 0x80080
	global_load_lds_dwordx4 v[0:1], off
	v_lshl_add_u64 v[0:1], v[2:3], 0, s[34:35]
	s_mov_b32 m0, s80
	s_addc_u32 s5, s77, 0
	global_load_lds_dwordx4 v[0:1], off
	s_add_i32 m0, s31, 0x1c000
	v_lshl_add_u64 v[0:1], s[4:5], 0, v[130:131]
	global_load_lds_dwordx4 v[0:1], off
	v_lshl_add_u64 v[0:1], s[4:5], 0, v[134:135]
	s_add_i32 m0, s31, 0x1e000
	v_lshlrev_b32_e32 v3, 2, v8
	global_load_lds_dwordx4 v[0:1], off
	v_lshrrev_b32_e32 v1, 1, v8
	v_and_b32_e32 v1, 24, v1
	v_and_b32_e32 v0, 15, v8
	v_lshlrev_b32_e32 v2, 1, v1
	v_lshl_or_b32 v2, v0, 6, v2
	v_and_b32_e32 v3, 32, v3
	v_lshl_or_b32 v161, s1, 6, v0
	v_bitop3_b32 v4, v2, s6, v3 bitop3:0xde
	v_bitop3_b32 v162, v2, s7, v3 bitop3:0xde
	v_add_u32_e32 v253, 0x18000, v162
	v_add_u32_e32 v254, 0x1c000, v162
	v_cmp_eq_u32_e64 s[6:7], 0, v0
	v_lshlrev_b32_e32 v0, 15, v9
	v_and_b32_e32 v0, 0xffff0000, v0
	v_or_b32_e32 v163, s3, v1
	v_lshl_add_u32 v0, v10, 12, v0
	v_and_b32_e32 v1, 1, v9
	v_lshl_or_b32 v0, v1, 6, v0
	v_lshl_add_u32 v138, v11, 1, v0
	v_lshlrev_b32_e32 v0, 15, v12
	v_and_b32_e32 v0, 0xffff0000, v0
	s_waitcnt vmcnt(6)
	s_cmpk_lt_u32 s0, 0x100
	v_lshl_add_u32 v0, v13, 12, v0
	v_and_b32_e32 v1, 1, v12
	s_cselect_b64 s[36:37], -1, 0
	v_lshl_or_b32 v0, v1, 6, v0
	s_add_i32 s81, 0, 0x10000
	s_add_i32 s83, 0, 0x14000
	v_or_b32_e32 v164, 0xffffa200, v163
	v_add_u32_e32 v165, 0x5a00, v161
	v_mov_b32_e32 v139, v137
	v_lshl_add_u32 v140, v14, 1, v0
	v_mov_b32_e32 v141, v137
	v_mov_b64_e32 v[142:143], 0x400
	v_mov_b64_e32 v[144:145], 0x3ff
	v_add_u32_e32 v166, s81, v162
	v_add_u32_e32 v167, s83, v162
	v_add_u32_e32 v168, 0, v4
	s_mov_b32 s38, 0x3e6d3388
	s_mov_b32 s40, 0x3f07dc22
	s_mov_b32 s42, 0xbf3a00e3
	s_mov_b32 s44, 0x3f35f0e3
	s_mov_b32 s46, 0xbe11a98e
	s_mov_b32 s48, 0x3e027906
	s_mov_b32 s50, 0xbf38aa3b
	s_mov_b32 s84, 0x50000
	s_mov_b64 s[52:53], 0x58000
	s_mov_b32 s85, 0x58000
	s_mov_b64 s[54:55], 0x400000
	s_mov_b32 s86, 0x400000
	s_mov_b64 s[56:57], 0x480000
	s_mov_b32 s87, 0x480000
	s_mov_b64 s[58:59], 0x500000
	s_mov_b32 s88, 0x500000
	s_mov_b64 s[60:61], 0x580000
	s_mov_b32 s89, 0x580000
	s_mov_b32 s8, s9
	s_barrier
	s_branch .LBB0_261

.LBB0_271:
	s_ashr_i32 s63, s62, 31
	s_lshl_b64 s[0:1], s[62:63], 20
	s_add_u32 s66, s49, s0
	s_addc_u32 s67, s82, s1
	s_and_b64 s[0:1], s[4:5], exec
	s_cselect_b32 s0, s67, s75
	s_cselect_b32 s1, s66, s74
	s_ashr_i32 s65, s64, 31
	s_lshl_b64 s[68:69], s[64:65], 20
	s_add_u32 s68, s45, s68
	s_addc_u32 s69, s47, s69
	s_and_b64 s[78:79], s[4:5], exec
	s_cselect_b32 s3, s69, s77
	s_cselect_b32 s63, s68, s76
	s_add_u32 s74, s74, 0x80080
	s_addc_u32 s75, s75, 0
	s_add_u32 s65, s76, 0x100
	s_addc_u32 s71, s77, 0
	s_mov_b32 s90, -2
	s_waitcnt vmcnt(0)
	ds_read_b128 v[146:149], v166
	ds_read_b128 v[150:153], v166 offset:1024
	ds_read_b128 v[154:157], v166 offset:2048
	ds_read_b128 v[170:173], v166 offset:3072
	ds_read_b128 v[174:177], v167
	ds_read_b128 v[178:181], v167 offset:1024
	ds_read_b128 v[182:185], v167 offset:2048
	ds_read_b128 v[186:189], v167 offset:3072
	s_add_u32 s76, s74, 0xfff80080
	s_addc_u32 s77, s75, -1
	s_cmp_eq_u32 s90, 28
	s_cselect_b32 s79, s0, s77
	s_cselect_b32 s78, s1, s76
	s_cselect_b32 s77, s3, s71
	s_cselect_b32 s76, s63, s65
	s_add_i32 m0, s31, 0xc000
	ds_read_b128 v[190:193], v168
	ds_read_b128 v[194:197], v168 offset:1024
	ds_read_b128 v[198:201], v168 offset:2048
	ds_read_b128 v[202:205], v168 offset:3072
	ds_read_b128 v[206:209], v168 offset:4096
	ds_read_b128 v[214:217], v168 offset:5120
	ds_read_b128 v[218:221], v168 offset:6144
	ds_read_b128 v[222:225], v168 offset:7168
	global_load_lds_dwordx4 v138, s[74:75]
	s_add_i32 m0, s31, 0xe000
	s_nop 0
	global_load_lds_dwordx4 v140, s[74:75]
	s_waitcnt vmcnt(8)
	s_waitcnt lgkmcnt(0)
	s_setprio 1
	s_barrier
	v_mfma_f32_16x16x32_bf16 v[124:127], v[146:149], v[190:193], 0
	v_mfma_f32_16x16x32_bf16 v[120:123], v[154:157], v[190:193], 0
	v_mfma_f32_16x16x32_bf16 v[108:111], v[146:149], v[198:201], 0
	v_mfma_f32_16x16x32_bf16 v[104:107], v[154:157], v[198:201], 0
	v_mfma_f32_16x16x32_bf16 v[92:95], v[146:149], v[206:209], 0
	v_mfma_f32_16x16x32_bf16 v[88:91], v[154:157], v[206:209], 0
	v_mfma_f32_16x16x32_bf16 v[76:79], v[146:149], v[218:221], 0
	v_mfma_f32_16x16x32_bf16 v[72:75], v[154:157], v[218:221], 0
	v_mfma_f32_16x16x32_bf16 v[124:127], v[150:153], v[194:197], v[124:127]
	v_mfma_f32_16x16x32_bf16 v[120:123], v[170:173], v[194:197], v[120:123]
	v_mfma_f32_16x16x32_bf16 v[108:111], v[150:153], v[202:205], v[108:111]
	v_mfma_f32_16x16x32_bf16 v[104:107], v[170:173], v[202:205], v[104:107]
	v_mfma_f32_16x16x32_bf16 v[92:95], v[150:153], v[214:217], v[92:95]
	v_mfma_f32_16x16x32_bf16 v[88:91], v[170:173], v[214:217], v[88:91]
	v_mfma_f32_16x16x32_bf16 v[76:79], v[150:153], v[222:225], v[76:79]
	v_mfma_f32_16x16x32_bf16 v[72:75], v[170:173], v[222:225], v[72:75]
	s_setprio 0
	s_setprio 1
	v_mfma_f32_16x16x32_bf16 v[116:119], v[174:177], v[190:193], 0
	v_mfma_f32_16x16x32_bf16 v[112:115], v[182:185], v[190:193], 0
	v_mfma_f32_16x16x32_bf16 v[100:103], v[174:177], v[198:201], 0
	v_mfma_f32_16x16x32_bf16 v[96:99], v[182:185], v[198:201], 0
	v_mfma_f32_16x16x32_bf16 v[84:87], v[174:177], v[206:209], 0
	v_mfma_f32_16x16x32_bf16 v[80:83], v[182:185], v[206:209], 0
	v_mfma_f32_16x16x32_bf16 v[68:71], v[174:177], v[218:221], 0
	v_mfma_f32_16x16x32_bf16 v[64:67], v[182:185], v[218:221], 0
	v_mfma_f32_16x16x32_bf16 v[116:119], v[178:181], v[194:197], v[116:119]
	v_mfma_f32_16x16x32_bf16 v[112:115], v[186:189], v[194:197], v[112:115]
	v_mfma_f32_16x16x32_bf16 v[100:103], v[178:181], v[202:205], v[100:103]
	v_mfma_f32_16x16x32_bf16 v[96:99], v[186:189], v[202:205], v[96:99]
	v_mfma_f32_16x16x32_bf16 v[84:87], v[178:181], v[214:217], v[84:87]
	v_mfma_f32_16x16x32_bf16 v[80:83], v[186:189], v[214:217], v[80:83]
	v_mfma_f32_16x16x32_bf16 v[68:71], v[178:181], v[222:225], v[68:71]
	v_mfma_f32_16x16x32_bf16 v[64:67], v[186:189], v[222:225], v[64:67]
	s_setprio 0
	s_barrier
	s_add_i32 s91, s81, s30
	s_add_u32 s98, s76, s34
	s_addc_u32 s99, s77, s35
	s_mov_b32 m0, s91
	ds_read_b128 v[190:193], v168 offset:16384
	ds_read_b128 v[194:197], v168 offset:17408
	ds_read_b128 v[198:201], v168 offset:18432
	ds_read_b128 v[202:205], v168 offset:19456
	ds_read_b128 v[206:209], v168 offset:20480
	ds_read_b128 v[214:217], v168 offset:21504
	ds_read_b128 v[218:221], v168 offset:22528
	ds_read_b128 v[222:225], v168 offset:23552
	global_load_lds_dwordx4 v130, s[76:77]
	s_add_i32 m0, s91, 0x2000
	s_add_u32 s92, s76, 0x80000
	s_addc_u32 s93, s77, 0
	s_add_i32 s91, s83, s30
	global_load_lds_dwordx4 v134, s[76:77]
	s_mov_b32 m0, s91
	s_add_u32 s100, s78, s34
	s_addc_u32 s101, s79, s35
	global_load_lds_dwordx4 v130, s[92:93]
	s_add_i32 m0, s91, 0x2000
	s_nop 0
	global_load_lds_dwordx4 v134, s[92:93]
	s_mov_b32 m0, s31
	s_nop 0
	global_load_lds_dwordx4 v128, s[78:79]
	s_mov_b32 m0, s51
	s_nop 0
	global_load_lds_dwordx4 v132, s[78:79]
	s_waitcnt vmcnt(8)
	s_waitcnt lgkmcnt(0)
	s_setprio 1
	s_barrier
	v_mfma_f32_16x16x32_bf16 v[60:63], v[146:149], v[190:193], 0
	v_mfma_f32_16x16x32_bf16 v[56:59], v[154:157], v[190:193], 0
	v_mfma_f32_16x16x32_bf16 v[44:47], v[146:149], v[198:201], 0
	v_mfma_f32_16x16x32_bf16 v[40:43], v[154:157], v[198:201], 0
	v_mfma_f32_16x16x32_bf16 v[28:31], v[146:149], v[206:209], 0
	v_mfma_f32_16x16x32_bf16 v[24:27], v[154:157], v[206:209], 0
	v_mfma_f32_16x16x32_bf16 v[12:15], v[146:149], v[218:221], 0
	v_mfma_f32_16x16x32_bf16 v[8:11], v[154:157], v[218:221], 0
	v_mfma_f32_16x16x32_bf16 v[60:63], v[150:153], v[194:197], v[60:63]
	v_mfma_f32_16x16x32_bf16 v[56:59], v[170:173], v[194:197], v[56:59]
	v_mfma_f32_16x16x32_bf16 v[44:47], v[150:153], v[202:205], v[44:47]
	v_mfma_f32_16x16x32_bf16 v[40:43], v[170:173], v[202:205], v[40:43]
	v_mfma_f32_16x16x32_bf16 v[28:31], v[150:153], v[214:217], v[28:31]
	v_mfma_f32_16x16x32_bf16 v[24:27], v[170:173], v[214:217], v[24:27]
	v_mfma_f32_16x16x32_bf16 v[12:15], v[150:153], v[222:225], v[12:15]
	v_mfma_f32_16x16x32_bf16 v[8:11], v[170:173], v[222:225], v[8:11]
	s_setprio 0
	s_setprio 1
	v_mfma_f32_16x16x32_bf16 v[52:55], v[174:177], v[190:193], 0
	v_mfma_f32_16x16x32_bf16 v[48:51], v[182:185], v[190:193], 0
	v_mfma_f32_16x16x32_bf16 v[36:39], v[174:177], v[198:201], 0
	v_mfma_f32_16x16x32_bf16 v[32:35], v[182:185], v[198:201], 0
	v_mfma_f32_16x16x32_bf16 v[20:23], v[174:177], v[206:209], 0
	v_mfma_f32_16x16x32_bf16 v[16:19], v[182:185], v[206:209], 0
	v_mfma_f32_16x16x32_bf16 v[4:7], v[174:177], v[218:221], 0
	v_mfma_f32_16x16x32_bf16 v[0:3], v[182:185], v[218:221], 0
	v_mfma_f32_16x16x32_bf16 v[52:55], v[178:181], v[194:197], v[52:55]
	v_mfma_f32_16x16x32_bf16 v[48:51], v[186:189], v[194:197], v[48:51]
	v_mfma_f32_16x16x32_bf16 v[36:39], v[178:181], v[202:205], v[36:39]
	v_mfma_f32_16x16x32_bf16 v[32:35], v[186:189], v[202:205], v[32:35]
	v_mfma_f32_16x16x32_bf16 v[20:23], v[178:181], v[214:217], v[20:23]
	v_mfma_f32_16x16x32_bf16 v[16:19], v[186:189], v[214:217], v[16:19]
	v_mfma_f32_16x16x32_bf16 v[4:7], v[178:181], v[222:225], v[4:7]
	v_mfma_f32_16x16x32_bf16 v[0:3], v[186:189], v[222:225], v[0:3]
	s_setprio 0
	s_barrier
	s_add_i32 s91, 0, 0x18000
	s_add_i32 s92, 0, 0x1c000
	ds_read_b128 v[146:149], v253
	ds_read_b128 v[150:153], v253 offset:1024
	ds_read_b128 v[154:157], v253 offset:2048
	ds_read_b128 v[170:173], v253 offset:3072
	ds_read_b128 v[174:177], v254
	ds_read_b128 v[178:181], v254 offset:1024
	ds_read_b128 v[182:185], v254 offset:2048
	ds_read_b128 v[186:189], v254 offset:3072
	s_add_u32 s78, s78, 0x80000
	s_addc_u32 s79, s79, 0
	s_mov_b32 m0, s28
	ds_read_b128 v[190:193], v168 offset:32768
	ds_read_b128 v[194:197], v168 offset:33792
	ds_read_b128 v[198:201], v168 offset:34816
	ds_read_b128 v[202:205], v168 offset:35840
	ds_read_b128 v[206:209], v168 offset:36864
	ds_read_b128 v[214:217], v168 offset:37888
	ds_read_b128 v[218:221], v168 offset:38912
	ds_read_b128 v[222:225], v168 offset:39936
	global_load_lds_dwordx4 v128, s[78:79]
	s_mov_b32 m0, s29
	s_nop 0
	global_load_lds_dwordx4 v132, s[78:79]
	s_waitcnt vmcnt(8)
	s_waitcnt lgkmcnt(0)
	s_setprio 1
	s_barrier
	v_mfma_f32_16x16x32_bf16 v[124:127], v[146:149], v[190:193], v[124:127]
	v_mfma_f32_16x16x32_bf16 v[120:123], v[154:157], v[190:193], v[120:123]
	v_mfma_f32_16x16x32_bf16 v[108:111], v[146:149], v[198:201], v[108:111]
	v_mfma_f32_16x16x32_bf16 v[104:107], v[154:157], v[198:201], v[104:107]
	v_mfma_f32_16x16x32_bf16 v[92:95], v[146:149], v[206:209], v[92:95]
	v_mfma_f32_16x16x32_bf16 v[88:91], v[154:157], v[206:209], v[88:91]
	v_mfma_f32_16x16x32_bf16 v[76:79], v[146:149], v[218:221], v[76:79]
	v_mfma_f32_16x16x32_bf16 v[72:75], v[154:157], v[218:221], v[72:75]
	v_mfma_f32_16x16x32_bf16 v[124:127], v[150:153], v[194:197], v[124:127]
	v_mfma_f32_16x16x32_bf16 v[120:123], v[170:173], v[194:197], v[120:123]
	v_mfma_f32_16x16x32_bf16 v[108:111], v[150:153], v[202:205], v[108:111]
	v_mfma_f32_16x16x32_bf16 v[104:107], v[170:173], v[202:205], v[104:107]
	v_mfma_f32_16x16x32_bf16 v[92:95], v[150:153], v[214:217], v[92:95]
	v_mfma_f32_16x16x32_bf16 v[88:91], v[170:173], v[214:217], v[88:91]
	v_mfma_f32_16x16x32_bf16 v[76:79], v[150:153], v[222:225], v[76:79]
	v_mfma_f32_16x16x32_bf16 v[72:75], v[170:173], v[222:225], v[72:75]
	s_setprio 0
	s_setprio 1
	v_mfma_f32_16x16x32_bf16 v[116:119], v[174:177], v[190:193], v[116:119]
	v_mfma_f32_16x16x32_bf16 v[112:115], v[182:185], v[190:193], v[112:115]
	v_mfma_f32_16x16x32_bf16 v[100:103], v[174:177], v[198:201], v[100:103]
	v_mfma_f32_16x16x32_bf16 v[96:99], v[182:185], v[198:201], v[96:99]
	v_mfma_f32_16x16x32_bf16 v[84:87], v[174:177], v[206:209], v[84:87]
	v_mfma_f32_16x16x32_bf16 v[80:83], v[182:185], v[206:209], v[80:83]
	v_mfma_f32_16x16x32_bf16 v[68:71], v[174:177], v[218:221], v[68:71]
	v_mfma_f32_16x16x32_bf16 v[64:67], v[182:185], v[218:221], v[64:67]
	v_mfma_f32_16x16x32_bf16 v[116:119], v[178:181], v[194:197], v[116:119]
	v_mfma_f32_16x16x32_bf16 v[112:115], v[186:189], v[194:197], v[112:115]
	v_mfma_f32_16x16x32_bf16 v[100:103], v[178:181], v[202:205], v[100:103]
	v_mfma_f32_16x16x32_bf16 v[96:99], v[186:189], v[202:205], v[96:99]
	v_mfma_f32_16x16x32_bf16 v[84:87], v[178:181], v[214:217], v[84:87]
	v_mfma_f32_16x16x32_bf16 v[80:83], v[186:189], v[214:217], v[80:83]
	v_mfma_f32_16x16x32_bf16 v[68:71], v[178:181], v[222:225], v[68:71]
	v_mfma_f32_16x16x32_bf16 v[64:67], v[186:189], v[222:225], v[64:67]
	s_setprio 0
	s_barrier
	s_add_i32 s78, s91, s30
	s_mov_b32 m0, s78
	ds_read_b128 v[190:193], v168 offset:49152
	ds_read_b128 v[194:197], v168 offset:50176
	ds_read_b128 v[198:201], v168 offset:51200
	ds_read_b128 v[202:205], v168 offset:52224
	ds_read_b128 v[206:209], v168 offset:53248
	ds_read_b128 v[214:217], v168 offset:54272
	ds_read_b128 v[218:221], v168 offset:55296
	ds_read_b128 v[222:225], v168 offset:56320
	global_load_lds_dwordx4 v130, s[98:99]
	s_add_i32 m0, s78, 0x2000
	s_add_u32 s76, s76, 0x80080
	s_addc_u32 s77, s77, 0
	s_add_i32 s78, s92, s30
	global_load_lds_dwordx4 v134, s[98:99]
	s_mov_b32 m0, s78
	s_nop 0
	global_load_lds_dwordx4 v130, s[76:77]
	s_add_i32 m0, s78, 0x2000
	s_nop 0
	global_load_lds_dwordx4 v134, s[76:77]
	s_mov_b32 m0, s73
	s_nop 0
	global_load_lds_dwordx4 v128, s[100:101]
	s_mov_b32 m0, s80
	s_nop 0
	global_load_lds_dwordx4 v132, s[100:101]
	s_waitcnt vmcnt(8)
	s_waitcnt lgkmcnt(0)
	s_setprio 1
	s_barrier
	v_mfma_f32_16x16x32_bf16 v[60:63], v[146:149], v[190:193], v[60:63]
	v_mfma_f32_16x16x32_bf16 v[56:59], v[154:157], v[190:193], v[56:59]
	v_mfma_f32_16x16x32_bf16 v[44:47], v[146:149], v[198:201], v[44:47]
	v_mfma_f32_16x16x32_bf16 v[40:43], v[154:157], v[198:201], v[40:43]
	v_mfma_f32_16x16x32_bf16 v[28:31], v[146:149], v[206:209], v[28:31]
	v_mfma_f32_16x16x32_bf16 v[24:27], v[154:157], v[206:209], v[24:27]
	v_mfma_f32_16x16x32_bf16 v[12:15], v[146:149], v[218:221], v[12:15]
	v_mfma_f32_16x16x32_bf16 v[8:11], v[154:157], v[218:221], v[8:11]
	v_mfma_f32_16x16x32_bf16 v[60:63], v[150:153], v[194:197], v[60:63]
	v_mfma_f32_16x16x32_bf16 v[56:59], v[170:173], v[194:197], v[56:59]
	v_mfma_f32_16x16x32_bf16 v[44:47], v[150:153], v[202:205], v[44:47]
	v_mfma_f32_16x16x32_bf16 v[40:43], v[170:173], v[202:205], v[40:43]
	v_mfma_f32_16x16x32_bf16 v[28:31], v[150:153], v[214:217], v[28:31]
	v_mfma_f32_16x16x32_bf16 v[24:27], v[170:173], v[214:217], v[24:27]
	v_mfma_f32_16x16x32_bf16 v[12:15], v[150:153], v[222:225], v[12:15]
	v_mfma_f32_16x16x32_bf16 v[8:11], v[170:173], v[222:225], v[8:11]
	s_setprio 0
	s_setprio 1
	v_mfma_f32_16x16x32_bf16 v[52:55], v[174:177], v[190:193], v[52:55]
	v_mfma_f32_16x16x32_bf16 v[48:51], v[182:185], v[190:193], v[48:51]
	v_mfma_f32_16x16x32_bf16 v[36:39], v[174:177], v[198:201], v[36:39]
	v_mfma_f32_16x16x32_bf16 v[32:35], v[182:185], v[198:201], v[32:35]
	v_mfma_f32_16x16x32_bf16 v[20:23], v[174:177], v[206:209], v[20:23]
	v_mfma_f32_16x16x32_bf16 v[16:19], v[182:185], v[206:209], v[16:19]
	v_mfma_f32_16x16x32_bf16 v[4:7], v[174:177], v[218:221], v[4:7]
	v_mfma_f32_16x16x32_bf16 v[0:3], v[182:185], v[218:221], v[0:3]
	v_mfma_f32_16x16x32_bf16 v[52:55], v[178:181], v[194:197], v[52:55]
	v_mfma_f32_16x16x32_bf16 v[48:51], v[186:189], v[194:197], v[48:51]
	v_mfma_f32_16x16x32_bf16 v[36:39], v[178:181], v[202:205], v[36:39]
	v_mfma_f32_16x16x32_bf16 v[32:35], v[186:189], v[202:205], v[32:35]
	v_mfma_f32_16x16x32_bf16 v[20:23], v[178:181], v[214:217], v[20:23]
	v_mfma_f32_16x16x32_bf16 v[16:19], v[186:189], v[214:217], v[16:19]
	v_mfma_f32_16x16x32_bf16 v[4:7], v[178:181], v[222:225], v[4:7]
	v_mfma_f32_16x16x32_bf16 v[0:3], v[186:189], v[222:225], v[0:3]
	s_setprio 0
	s_barrier
	s_add_i32 s90, s90, 2
	s_add_u32 s74, s74, 0x100
	s_addc_u32 s75, s75, 0
	s_add_u32 s65, s65, 0x100
	s_addc_u32 s71, s71, 0
	s_cmp_gt_u32 s90, 29
.LBB0_272:
	ds_read_b128 v[146:149], v166
	ds_read_b128 v[150:153], v166 offset:1024
	ds_read_b128 v[154:157], v166 offset:2048
	ds_read_b128 v[170:173], v166 offset:3072
	ds_read_b128 v[174:177], v167
	ds_read_b128 v[178:181], v167 offset:1024
	ds_read_b128 v[182:185], v167 offset:2048
	ds_read_b128 v[186:189], v167 offset:3072
	s_add_u32 s76, s74, 0xfff80080
	s_addc_u32 s77, s75, -1
	s_cmp_eq_u32 s90, 28
	s_cselect_b32 s79, s0, s77
	s_cselect_b32 s78, s1, s76
	s_cselect_b32 s77, s3, s71
	s_cselect_b32 s76, s63, s65
	s_add_i32 m0, s31, 0xc000
	ds_read_b128 v[190:193], v168
	ds_read_b128 v[194:197], v168 offset:1024
	ds_read_b128 v[198:201], v168 offset:2048
	ds_read_b128 v[202:205], v168 offset:3072
	ds_read_b128 v[206:209], v168 offset:4096
	ds_read_b128 v[214:217], v168 offset:5120
	ds_read_b128 v[218:221], v168 offset:6144
	ds_read_b128 v[222:225], v168 offset:7168
	global_load_lds_dwordx4 v138, s[74:75]
	s_add_i32 m0, s31, 0xe000
	s_nop 0
	global_load_lds_dwordx4 v140, s[74:75]
	s_waitcnt vmcnt(8)
	s_waitcnt lgkmcnt(0)
	s_setprio 1
	s_barrier
	v_mfma_f32_16x16x32_bf16 v[124:127], v[146:149], v[190:193], v[124:127]
	v_mfma_f32_16x16x32_bf16 v[120:123], v[154:157], v[190:193], v[120:123]
	v_mfma_f32_16x16x32_bf16 v[108:111], v[146:149], v[198:201], v[108:111]
	v_mfma_f32_16x16x32_bf16 v[104:107], v[154:157], v[198:201], v[104:107]
	v_mfma_f32_16x16x32_bf16 v[92:95], v[146:149], v[206:209], v[92:95]
	v_mfma_f32_16x16x32_bf16 v[88:91], v[154:157], v[206:209], v[88:91]
	v_mfma_f32_16x16x32_bf16 v[76:79], v[146:149], v[218:221], v[76:79]
	v_mfma_f32_16x16x32_bf16 v[72:75], v[154:157], v[218:221], v[72:75]
	v_mfma_f32_16x16x32_bf16 v[124:127], v[150:153], v[194:197], v[124:127]
	v_mfma_f32_16x16x32_bf16 v[120:123], v[170:173], v[194:197], v[120:123]
	v_mfma_f32_16x16x32_bf16 v[108:111], v[150:153], v[202:205], v[108:111]
	v_mfma_f32_16x16x32_bf16 v[104:107], v[170:173], v[202:205], v[104:107]
	v_mfma_f32_16x16x32_bf16 v[92:95], v[150:153], v[214:217], v[92:95]
	v_mfma_f32_16x16x32_bf16 v[88:91], v[170:173], v[214:217], v[88:91]
	v_mfma_f32_16x16x32_bf16 v[76:79], v[150:153], v[222:225], v[76:79]
	v_mfma_f32_16x16x32_bf16 v[72:75], v[170:173], v[222:225], v[72:75]
	s_setprio 0
	s_setprio 1
	v_mfma_f32_16x16x32_bf16 v[116:119], v[174:177], v[190:193], v[116:119]
	v_mfma_f32_16x16x32_bf16 v[112:115], v[182:185], v[190:193], v[112:115]
	v_mfma_f32_16x16x32_bf16 v[100:103], v[174:177], v[198:201], v[100:103]
	v_mfma_f32_16x16x32_bf16 v[96:99], v[182:185], v[198:201], v[96:99]
	v_mfma_f32_16x16x32_bf16 v[84:87], v[174:177], v[206:209], v[84:87]
	v_mfma_f32_16x16x32_bf16 v[80:83], v[182:185], v[206:209], v[80:83]
	v_mfma_f32_16x16x32_bf16 v[68:71], v[174:177], v[218:221], v[68:71]
	v_mfma_f32_16x16x32_bf16 v[64:67], v[182:185], v[218:221], v[64:67]
	v_mfma_f32_16x16x32_bf16 v[116:119], v[178:181], v[194:197], v[116:119]
	v_mfma_f32_16x16x32_bf16 v[112:115], v[186:189], v[194:197], v[112:115]
	v_mfma_f32_16x16x32_bf16 v[100:103], v[178:181], v[202:205], v[100:103]
	v_mfma_f32_16x16x32_bf16 v[96:99], v[186:189], v[202:205], v[96:99]
	v_mfma_f32_16x16x32_bf16 v[84:87], v[178:181], v[214:217], v[84:87]
	v_mfma_f32_16x16x32_bf16 v[80:83], v[186:189], v[214:217], v[80:83]
	v_mfma_f32_16x16x32_bf16 v[68:71], v[178:181], v[222:225], v[68:71]
	v_mfma_f32_16x16x32_bf16 v[64:67], v[186:189], v[222:225], v[64:67]
	s_setprio 0
	s_barrier
	s_add_i32 s91, s81, s30
	s_add_u32 s98, s76, s34
	s_addc_u32 s99, s77, s35
	s_mov_b32 m0, s91
	ds_read_b128 v[190:193], v168 offset:16384
	ds_read_b128 v[194:197], v168 offset:17408
	ds_read_b128 v[198:201], v168 offset:18432
	ds_read_b128 v[202:205], v168 offset:19456
	ds_read_b128 v[206:209], v168 offset:20480
	ds_read_b128 v[214:217], v168 offset:21504
	ds_read_b128 v[218:221], v168 offset:22528
	ds_read_b128 v[222:225], v168 offset:23552
	global_load_lds_dwordx4 v130, s[76:77]
	s_add_i32 m0, s91, 0x2000
	s_add_u32 s92, s76, 0x80000
	s_addc_u32 s93, s77, 0
	s_add_i32 s91, s83, s30
	global_load_lds_dwordx4 v134, s[76:77]
	s_mov_b32 m0, s91
	s_add_u32 s100, s78, s34
	s_addc_u32 s101, s79, s35
	global_load_lds_dwordx4 v130, s[92:93]
	s_add_i32 m0, s91, 0x2000
	s_nop 0
	global_load_lds_dwordx4 v134, s[92:93]
	s_mov_b32 m0, s31
	s_nop 0
	global_load_lds_dwordx4 v128, s[78:79]
	s_mov_b32 m0, s51
	s_nop 0
	global_load_lds_dwordx4 v132, s[78:79]
	s_waitcnt vmcnt(8)
	s_waitcnt lgkmcnt(0)
	s_setprio 1
	s_barrier
	v_mfma_f32_16x16x32_bf16 v[60:63], v[146:149], v[190:193], v[60:63]
	v_mfma_f32_16x16x32_bf16 v[56:59], v[154:157], v[190:193], v[56:59]
	v_mfma_f32_16x16x32_bf16 v[44:47], v[146:149], v[198:201], v[44:47]
	v_mfma_f32_16x16x32_bf16 v[40:43], v[154:157], v[198:201], v[40:43]
	v_mfma_f32_16x16x32_bf16 v[28:31], v[146:149], v[206:209], v[28:31]
	v_mfma_f32_16x16x32_bf16 v[24:27], v[154:157], v[206:209], v[24:27]
	v_mfma_f32_16x16x32_bf16 v[12:15], v[146:149], v[218:221], v[12:15]
	v_mfma_f32_16x16x32_bf16 v[8:11], v[154:157], v[218:221], v[8:11]
	v_mfma_f32_16x16x32_bf16 v[60:63], v[150:153], v[194:197], v[60:63]
	v_mfma_f32_16x16x32_bf16 v[56:59], v[170:173], v[194:197], v[56:59]
	v_mfma_f32_16x16x32_bf16 v[44:47], v[150:153], v[202:205], v[44:47]
	v_mfma_f32_16x16x32_bf16 v[40:43], v[170:173], v[202:205], v[40:43]
	v_mfma_f32_16x16x32_bf16 v[28:31], v[150:153], v[214:217], v[28:31]
	v_mfma_f32_16x16x32_bf16 v[24:27], v[170:173], v[214:217], v[24:27]
	v_mfma_f32_16x16x32_bf16 v[12:15], v[150:153], v[222:225], v[12:15]
	v_mfma_f32_16x16x32_bf16 v[8:11], v[170:173], v[222:225], v[8:11]
	s_setprio 0
	s_setprio 1
	v_mfma_f32_16x16x32_bf16 v[52:55], v[174:177], v[190:193], v[52:55]
	v_mfma_f32_16x16x32_bf16 v[48:51], v[182:185], v[190:193], v[48:51]
	v_mfma_f32_16x16x32_bf16 v[36:39], v[174:177], v[198:201], v[36:39]
	v_mfma_f32_16x16x32_bf16 v[32:35], v[182:185], v[198:201], v[32:35]
	v_mfma_f32_16x16x32_bf16 v[20:23], v[174:177], v[206:209], v[20:23]
	v_mfma_f32_16x16x32_bf16 v[16:19], v[182:185], v[206:209], v[16:19]
	v_mfma_f32_16x16x32_bf16 v[4:7], v[174:177], v[218:221], v[4:7]
	v_mfma_f32_16x16x32_bf16 v[0:3], v[182:185], v[218:221], v[0:3]
	v_mfma_f32_16x16x32_bf16 v[52:55], v[178:181], v[194:197], v[52:55]
	v_mfma_f32_16x16x32_bf16 v[48:51], v[186:189], v[194:197], v[48:51]
	v_mfma_f32_16x16x32_bf16 v[36:39], v[178:181], v[202:205], v[36:39]
	v_mfma_f32_16x16x32_bf16 v[32:35], v[186:189], v[202:205], v[32:35]
	v_mfma_f32_16x16x32_bf16 v[20:23], v[178:181], v[214:217], v[20:23]
	v_mfma_f32_16x16x32_bf16 v[16:19], v[186:189], v[214:217], v[16:19]
	v_mfma_f32_16x16x32_bf16 v[4:7], v[178:181], v[222:225], v[4:7]
	v_mfma_f32_16x16x32_bf16 v[0:3], v[186:189], v[222:225], v[0:3]
	s_setprio 0
	s_barrier
	s_add_i32 s91, 0, 0x18000
	s_add_i32 s92, 0, 0x1c000
	ds_read_b128 v[146:149], v253
	ds_read_b128 v[150:153], v253 offset:1024
	ds_read_b128 v[154:157], v253 offset:2048
	ds_read_b128 v[170:173], v253 offset:3072
	ds_read_b128 v[174:177], v254
	ds_read_b128 v[178:181], v254 offset:1024
	ds_read_b128 v[182:185], v254 offset:2048
	ds_read_b128 v[186:189], v254 offset:3072
	s_add_u32 s78, s78, 0x80000
	s_addc_u32 s79, s79, 0
	s_mov_b32 m0, s28
	ds_read_b128 v[190:193], v168 offset:32768
	ds_read_b128 v[194:197], v168 offset:33792
	ds_read_b128 v[198:201], v168 offset:34816
	ds_read_b128 v[202:205], v168 offset:35840
	ds_read_b128 v[206:209], v168 offset:36864
	ds_read_b128 v[214:217], v168 offset:37888
	ds_read_b128 v[218:221], v168 offset:38912
	ds_read_b128 v[222:225], v168 offset:39936
	global_load_lds_dwordx4 v128, s[78:79]
	s_mov_b32 m0, s29
	s_nop 0
	global_load_lds_dwordx4 v132, s[78:79]
	s_waitcnt vmcnt(8)
	s_waitcnt lgkmcnt(0)
	s_setprio 1
	s_barrier
	v_mfma_f32_16x16x32_bf16 v[124:127], v[146:149], v[190:193], v[124:127]
	v_mfma_f32_16x16x32_bf16 v[120:123], v[154:157], v[190:193], v[120:123]
	v_mfma_f32_16x16x32_bf16 v[108:111], v[146:149], v[198:201], v[108:111]
	v_mfma_f32_16x16x32_bf16 v[104:107], v[154:157], v[198:201], v[104:107]
	v_mfma_f32_16x16x32_bf16 v[92:95], v[146:149], v[206:209], v[92:95]
	v_mfma_f32_16x16x32_bf16 v[88:91], v[154:157], v[206:209], v[88:91]
	v_mfma_f32_16x16x32_bf16 v[76:79], v[146:149], v[218:221], v[76:79]
	v_mfma_f32_16x16x32_bf16 v[72:75], v[154:157], v[218:221], v[72:75]
	v_mfma_f32_16x16x32_bf16 v[124:127], v[150:153], v[194:197], v[124:127]
	v_mfma_f32_16x16x32_bf16 v[120:123], v[170:173], v[194:197], v[120:123]
	v_mfma_f32_16x16x32_bf16 v[108:111], v[150:153], v[202:205], v[108:111]
	v_mfma_f32_16x16x32_bf16 v[104:107], v[170:173], v[202:205], v[104:107]
	v_mfma_f32_16x16x32_bf16 v[92:95], v[150:153], v[214:217], v[92:95]
	v_mfma_f32_16x16x32_bf16 v[88:91], v[170:173], v[214:217], v[88:91]
	v_mfma_f32_16x16x32_bf16 v[76:79], v[150:153], v[222:225], v[76:79]
	v_mfma_f32_16x16x32_bf16 v[72:75], v[170:173], v[222:225], v[72:75]
	s_setprio 0
	s_setprio 1
	v_mfma_f32_16x16x32_bf16 v[116:119], v[174:177], v[190:193], v[116:119]
	v_mfma_f32_16x16x32_bf16 v[112:115], v[182:185], v[190:193], v[112:115]
	v_mfma_f32_16x16x32_bf16 v[100:103], v[174:177], v[198:201], v[100:103]
	v_mfma_f32_16x16x32_bf16 v[96:99], v[182:185], v[198:201], v[96:99]
	v_mfma_f32_16x16x32_bf16 v[84:87], v[174:177], v[206:209], v[84:87]
	v_mfma_f32_16x16x32_bf16 v[80:83], v[182:185], v[206:209], v[80:83]
	v_mfma_f32_16x16x32_bf16 v[68:71], v[174:177], v[218:221], v[68:71]
	v_mfma_f32_16x16x32_bf16 v[64:67], v[182:185], v[218:221], v[64:67]
	v_mfma_f32_16x16x32_bf16 v[116:119], v[178:181], v[194:197], v[116:119]
	v_mfma_f32_16x16x32_bf16 v[112:115], v[186:189], v[194:197], v[112:115]
	v_mfma_f32_16x16x32_bf16 v[100:103], v[178:181], v[202:205], v[100:103]
	v_mfma_f32_16x16x32_bf16 v[96:99], v[186:189], v[202:205], v[96:99]
	v_mfma_f32_16x16x32_bf16 v[84:87], v[178:181], v[214:217], v[84:87]
	v_mfma_f32_16x16x32_bf16 v[80:83], v[186:189], v[214:217], v[80:83]
	v_mfma_f32_16x16x32_bf16 v[68:71], v[178:181], v[222:225], v[68:71]
	v_mfma_f32_16x16x32_bf16 v[64:67], v[186:189], v[222:225], v[64:67]
	s_setprio 0
	s_barrier
	s_add_i32 s78, s91, s30
	s_mov_b32 m0, s78
	ds_read_b128 v[190:193], v168 offset:49152
	ds_read_b128 v[194:197], v168 offset:50176
	ds_read_b128 v[198:201], v168 offset:51200
	ds_read_b128 v[202:205], v168 offset:52224
	ds_read_b128 v[206:209], v168 offset:53248
	ds_read_b128 v[214:217], v168 offset:54272
	ds_read_b128 v[218:221], v168 offset:55296
	ds_read_b128 v[222:225], v168 offset:56320
	global_load_lds_dwordx4 v130, s[98:99]
	s_add_i32 m0, s78, 0x2000
	s_add_u32 s76, s76, 0x80080
	s_addc_u32 s77, s77, 0
	s_add_i32 s78, s92, s30
	global_load_lds_dwordx4 v134, s[98:99]
	s_mov_b32 m0, s78
	s_nop 0
	global_load_lds_dwordx4 v130, s[76:77]
	s_add_i32 m0, s78, 0x2000
	s_nop 0
	global_load_lds_dwordx4 v134, s[76:77]
	s_mov_b32 m0, s73
	s_nop 0
	global_load_lds_dwordx4 v128, s[100:101]
	s_mov_b32 m0, s80
	s_nop 0
	global_load_lds_dwordx4 v132, s[100:101]
	s_waitcnt vmcnt(8)
	s_waitcnt lgkmcnt(0)
	s_setprio 1
	s_barrier
	v_mfma_f32_16x16x32_bf16 v[60:63], v[146:149], v[190:193], v[60:63]
	v_mfma_f32_16x16x32_bf16 v[56:59], v[154:157], v[190:193], v[56:59]
	v_mfma_f32_16x16x32_bf16 v[44:47], v[146:149], v[198:201], v[44:47]
	v_mfma_f32_16x16x32_bf16 v[40:43], v[154:157], v[198:201], v[40:43]
	v_mfma_f32_16x16x32_bf16 v[28:31], v[146:149], v[206:209], v[28:31]
	v_mfma_f32_16x16x32_bf16 v[24:27], v[154:157], v[206:209], v[24:27]
	v_mfma_f32_16x16x32_bf16 v[12:15], v[146:149], v[218:221], v[12:15]
	v_mfma_f32_16x16x32_bf16 v[8:11], v[154:157], v[218:221], v[8:11]
	v_mfma_f32_16x16x32_bf16 v[60:63], v[150:153], v[194:197], v[60:63]
	v_mfma_f32_16x16x32_bf16 v[56:59], v[170:173], v[194:197], v[56:59]
	v_mfma_f32_16x16x32_bf16 v[44:47], v[150:153], v[202:205], v[44:47]
	v_mfma_f32_16x16x32_bf16 v[40:43], v[170:173], v[202:205], v[40:43]
	v_mfma_f32_16x16x32_bf16 v[28:31], v[150:153], v[214:217], v[28:31]
	v_mfma_f32_16x16x32_bf16 v[24:27], v[170:173], v[214:217], v[24:27]
	v_mfma_f32_16x16x32_bf16 v[12:15], v[150:153], v[222:225], v[12:15]
	v_mfma_f32_16x16x32_bf16 v[8:11], v[170:173], v[222:225], v[8:11]
	s_setprio 0
	s_setprio 1
	v_mfma_f32_16x16x32_bf16 v[52:55], v[174:177], v[190:193], v[52:55]
	v_mfma_f32_16x16x32_bf16 v[48:51], v[182:185], v[190:193], v[48:51]
	v_mfma_f32_16x16x32_bf16 v[36:39], v[174:177], v[198:201], v[36:39]
	v_mfma_f32_16x16x32_bf16 v[32:35], v[182:185], v[198:201], v[32:35]
	v_mfma_f32_16x16x32_bf16 v[20:23], v[174:177], v[206:209], v[20:23]
	v_mfma_f32_16x16x32_bf16 v[16:19], v[182:185], v[206:209], v[16:19]
	v_mfma_f32_16x16x32_bf16 v[4:7], v[174:177], v[218:221], v[4:7]
	v_mfma_f32_16x16x32_bf16 v[0:3], v[182:185], v[218:221], v[0:3]
	v_mfma_f32_16x16x32_bf16 v[52:55], v[178:181], v[194:197], v[52:55]
	v_mfma_f32_16x16x32_bf16 v[48:51], v[186:189], v[194:197], v[48:51]
	v_mfma_f32_16x16x32_bf16 v[36:39], v[178:181], v[202:205], v[36:39]
	v_mfma_f32_16x16x32_bf16 v[32:35], v[186:189], v[202:205], v[32:35]
	v_mfma_f32_16x16x32_bf16 v[20:23], v[178:181], v[214:217], v[20:23]
	v_mfma_f32_16x16x32_bf16 v[16:19], v[186:189], v[214:217], v[16:19]
	v_mfma_f32_16x16x32_bf16 v[4:7], v[178:181], v[222:225], v[4:7]
	v_mfma_f32_16x16x32_bf16 v[0:3], v[186:189], v[222:225], v[0:3]
	s_setprio 0
	s_barrier
	s_add_i32 s90, s90, 2
	s_add_u32 s74, s74, 0x100
	s_addc_u32 s75, s75, 0
	s_add_u32 s65, s65, 0x100
	s_addc_u32 s71, s71, 0
	s_cmp_gt_u32 s90, 29
	s_cbranch_scc0 .LBB0_272
	s_and_b64 vcc, exec, s[36:37]
	s_cbranch_vccz .LBB0_275
	s_barrier

.LBB0_533:
	s_add_u32 s14, s4, 0x120000
	s_addc_u32 s15, s5, 0
	s_add_u32 s16, s4, 0x140000
	s_addc_u32 s17, s5, 0
	s_add_u32 s18, s4, 0x10d00000
	s_addc_u32 s19, s5, 0
	s_lshl_b32 s3, s3, 5
	s_mov_b64 s[20:21], 0x80
	s_and_b32 s3, s3, 0x60
	s_add_i32 m0, s41, 0x18000
	v_lshl_add_u64 v[6:7], v[6:7], 0, s[20:21]
	s_lshl_b32 s6, s1, 13
	s_lshl_b32 s7, s3, 7
	s_waitcnt vmcnt(2)
	s_barrier
	global_load_lds_dwordx4 v[6:7], off
	v_lshl_add_u64 v[4:5], v[4:5], 0, s[20:21]
	s_add_i32 m0, s41, 0x1a000
	s_add_i32 s52, s41, 0x8000
	s_add_i32 s53, s41, 0xa000
	global_load_lds_dwordx4 v[4:5], off
	v_lshl_add_u64 v[0:1], v[0:1], 0, s[20:21]
	s_mov_b32 m0, s52
	s_add_u32 s4, s44, 0x80080
	global_load_lds_dwordx4 v[0:1], off
	v_lshl_add_u64 v[0:1], v[2:3], 0, s[20:21]
	s_mov_b32 m0, s53
	s_addc_u32 s5, s45, 0
	global_load_lds_dwordx4 v[0:1], off
	s_add_i32 m0, s41, 0x1c000
	v_lshl_add_u64 v[0:1], s[4:5], 0, v[178:179]
	global_load_lds_dwordx4 v[0:1], off
	v_lshl_add_u64 v[0:1], s[4:5], 0, v[182:183]
	s_add_i32 m0, s41, 0x1e000
	s_cmpk_lt_u32 s0, 0x100
	global_load_lds_dwordx4 v[0:1], off
	v_bfe_u32 v1, v8, 4, 2
	v_and_b32_e32 v0, 15, v8
	v_lshlrev_b32_e32 v2, 4, v1
	v_lshl_or_b32 v213, s1, 6, v0
	v_lshl_or_b32 v0, v0, 6, v2
	v_lshlrev_b32_e32 v2, 2, v8
	v_and_b32_e32 v2, 32, v2
	v_bitop3_b32 v3, v0, s6, v2 bitop3:0xde
	v_bitop3_b32 v214, v0, s7, v2 bitop3:0xde
	v_add_u32_e32 v253, 0x18000, v214
	v_add_u32_e32 v254, 0x1c000, v214
	v_lshlrev_b32_e32 v0, 15, v9
	v_and_b32_e32 v0, 0xffff0000, v0
	v_cmp_eq_u32_e64 s[4:5], 0, v1
	v_lshl_or_b32 v215, v1, 3, s3
	v_lshl_add_u32 v0, v10, 12, v0
	v_and_b32_e32 v1, 1, v9
	v_lshl_or_b32 v0, v1, 6, v0
	v_lshl_add_u32 v184, v11, 1, v0
	v_lshlrev_b32_e32 v0, 15, v12
	v_and_b32_e32 v0, 0xffff0000, v0
	v_lshl_add_u32 v0, v13, 12, v0
	v_and_b32_e32 v1, 1, v12
	s_waitcnt vmcnt(6)
	v_lshl_or_b32 v0, v1, 6, v0
	s_cselect_b64 s[22:23], -1, 0
	v_lshl_add_u32 v186, v14, 1, v0
	s_add_i32 s55, 0, 0x10000
	s_add_i32 s56, 0, 0x14000
	v_mbcnt_lo_u32_b32 v0, -1, 0
	s_ashr_i32 s54, s26, 31
	v_mov_b32_e32 v185, v179
	v_mov_b32_e32 v187, v179
	v_mov_b64_e32 v[188:189], 0x200
	v_mov_b64_e32 v[190:191], 0x1ff
	v_add_u32_e32 v216, s55, v214
	v_add_u32_e32 v217, s56, v214
	v_add_u32_e32 v218, 0, v3
	v_mov_b32_e32 v219, 0x358637bd
	s_mov_b32 s57, 0xf800000
	v_mov_b32_e32 v220, 0x260
	v_mbcnt_hi_u32_b32 v221, -1, v0
	s_barrier
	s_branch .LBB0_536

.LBB0_542:
	s_ashr_i32 s35, s34, 31
	s_lshl_b64 s[0:1], s[34:35], 20
	s_add_u32 s36, s29, s0
	s_addc_u32 s37, s30, s1
	s_and_b64 s[0:1], s[6:7], exec
	s_cselect_b32 s0, s37, s43
	s_cselect_b32 s1, s36, s42
	s_ashr_i32 s25, s24, 31
	s_lshl_b64 s[38:39], s[24:25], 20
	s_add_u32 s38, s27, s38
	s_addc_u32 s39, s28, s39
	s_and_b64 s[46:47], s[6:7], exec
	s_cselect_b32 s3, s39, s45
	s_cselect_b32 s9, s38, s44
	s_add_u32 s42, s42, 0x80080
	s_addc_u32 s43, s43, 0
	s_add_u32 s25, s44, 0x100
	s_addc_u32 s35, s45, 0
	s_mov_b32 s58, -2
	s_waitcnt lgkmcnt(0)
	s_waitcnt vmcnt(0)
	ds_read_b128 v[128:131], v216
	ds_read_b128 v[132:135], v216 offset:1024
	ds_read_b128 v[136:139], v216 offset:2048
	ds_read_b128 v[140:143], v216 offset:3072
	ds_read_b128 v[144:147], v217
	ds_read_b128 v[148:151], v217 offset:1024
	ds_read_b128 v[152:155], v217 offset:2048
	ds_read_b128 v[156:159], v217 offset:3072
	s_add_u32 s44, s42, 0xfff80080
	s_addc_u32 s45, s43, -1
	s_cmp_eq_u32 s58, 28
	s_cselect_b32 s47, s0, s45
	s_cselect_b32 s46, s1, s44
	s_cselect_b32 s45, s3, s35
	s_cselect_b32 s44, s9, s25
	s_add_i32 m0, s41, 0xc000
	ds_read_b128 v[160:163], v218
	ds_read_b128 v[164:167], v218 offset:1024
	ds_read_b128 v[168:171], v218 offset:2048
	ds_read_b128 v[172:175], v218 offset:3072
	ds_read_b128 v[192:195], v218 offset:4096
	ds_read_b128 v[196:199], v218 offset:5120
	ds_read_b128 v[200:203], v218 offset:6144
	ds_read_b128 v[204:207], v218 offset:7168
	global_load_lds_dwordx4 v184, s[42:43]
	s_add_i32 m0, s41, 0xe000
	s_nop 0
	global_load_lds_dwordx4 v186, s[42:43]
	s_waitcnt vmcnt(8)
	s_waitcnt lgkmcnt(0)
	s_setprio 1
	s_barrier
	v_mfma_f32_16x16x32_bf16 v[124:127], v[128:131], v[160:163], 0
	v_mfma_f32_16x16x32_bf16 v[120:123], v[136:139], v[160:163], 0
	v_mfma_f32_16x16x32_bf16 v[108:111], v[128:131], v[168:171], 0
	v_mfma_f32_16x16x32_bf16 v[104:107], v[136:139], v[168:171], 0
	v_mfma_f32_16x16x32_bf16 v[92:95], v[128:131], v[192:195], 0
	v_mfma_f32_16x16x32_bf16 v[88:91], v[136:139], v[192:195], 0
	v_mfma_f32_16x16x32_bf16 v[76:79], v[128:131], v[200:203], 0
	v_mfma_f32_16x16x32_bf16 v[72:75], v[136:139], v[200:203], 0
	v_mfma_f32_16x16x32_bf16 v[124:127], v[132:135], v[164:167], v[124:127]
	v_mfma_f32_16x16x32_bf16 v[120:123], v[140:143], v[164:167], v[120:123]
	v_mfma_f32_16x16x32_bf16 v[108:111], v[132:135], v[172:175], v[108:111]
	v_mfma_f32_16x16x32_bf16 v[104:107], v[140:143], v[172:175], v[104:107]
	v_mfma_f32_16x16x32_bf16 v[92:95], v[132:135], v[196:199], v[92:95]
	v_mfma_f32_16x16x32_bf16 v[88:91], v[140:143], v[196:199], v[88:91]
	v_mfma_f32_16x16x32_bf16 v[76:79], v[132:135], v[204:207], v[76:79]
	v_mfma_f32_16x16x32_bf16 v[72:75], v[140:143], v[204:207], v[72:75]
	s_setprio 0
	s_setprio 1
	v_mfma_f32_16x16x32_bf16 v[116:119], v[144:147], v[160:163], 0
	v_mfma_f32_16x16x32_bf16 v[112:115], v[152:155], v[160:163], 0
	v_mfma_f32_16x16x32_bf16 v[100:103], v[144:147], v[168:171], 0
	v_mfma_f32_16x16x32_bf16 v[96:99], v[152:155], v[168:171], 0
	v_mfma_f32_16x16x32_bf16 v[84:87], v[144:147], v[192:195], 0
	v_mfma_f32_16x16x32_bf16 v[80:83], v[152:155], v[192:195], 0
	v_mfma_f32_16x16x32_bf16 v[68:71], v[144:147], v[200:203], 0
	v_mfma_f32_16x16x32_bf16 v[64:67], v[152:155], v[200:203], 0
	v_mfma_f32_16x16x32_bf16 v[116:119], v[148:151], v[164:167], v[116:119]
	v_mfma_f32_16x16x32_bf16 v[112:115], v[156:159], v[164:167], v[112:115]
	v_mfma_f32_16x16x32_bf16 v[100:103], v[148:151], v[172:175], v[100:103]
	v_mfma_f32_16x16x32_bf16 v[96:99], v[156:159], v[172:175], v[96:99]
	v_mfma_f32_16x16x32_bf16 v[84:87], v[148:151], v[196:199], v[84:87]
	v_mfma_f32_16x16x32_bf16 v[80:83], v[156:159], v[196:199], v[80:83]
	v_mfma_f32_16x16x32_bf16 v[68:71], v[148:151], v[204:207], v[68:71]
	v_mfma_f32_16x16x32_bf16 v[64:67], v[156:159], v[204:207], v[64:67]
	s_setprio 0
	s_barrier
	s_add_i32 s59, s55, s31
	s_add_u32 s98, s44, s20
	s_addc_u32 s99, s45, s21
	s_mov_b32 m0, s59
	ds_read_b128 v[160:163], v218 offset:16384
	ds_read_b128 v[164:167], v218 offset:17408
	ds_read_b128 v[168:171], v218 offset:18432
	ds_read_b128 v[172:175], v218 offset:19456
	ds_read_b128 v[192:195], v218 offset:20480
	ds_read_b128 v[196:199], v218 offset:21504
	ds_read_b128 v[200:203], v218 offset:22528
	ds_read_b128 v[204:207], v218 offset:23552
	global_load_lds_dwordx4 v178, s[44:45]
	s_add_i32 m0, s59, 0x2000
	s_add_u32 s60, s44, 0x80000
	s_addc_u32 s61, s45, 0
	s_add_i32 s59, s56, s31
	global_load_lds_dwordx4 v182, s[44:45]
	s_mov_b32 m0, s59
	s_add_u32 s100, s46, s20
	s_addc_u32 s101, s47, s21
	global_load_lds_dwordx4 v178, s[60:61]
	s_add_i32 m0, s59, 0x2000
	s_nop 0
	global_load_lds_dwordx4 v182, s[60:61]
	s_mov_b32 m0, s41
	s_nop 0
	global_load_lds_dwordx4 v176, s[46:47]
	s_mov_b32 m0, s48
	s_nop 0
	global_load_lds_dwordx4 v180, s[46:47]
	s_waitcnt vmcnt(8)
	s_waitcnt lgkmcnt(0)
	s_setprio 1
	s_barrier
	v_mfma_f32_16x16x32_bf16 v[60:63], v[128:131], v[160:163], 0
	v_mfma_f32_16x16x32_bf16 v[56:59], v[136:139], v[160:163], 0
	v_mfma_f32_16x16x32_bf16 v[44:47], v[128:131], v[168:171], 0
	v_mfma_f32_16x16x32_bf16 v[40:43], v[136:139], v[168:171], 0
	v_mfma_f32_16x16x32_bf16 v[28:31], v[128:131], v[192:195], 0
	v_mfma_f32_16x16x32_bf16 v[24:27], v[136:139], v[192:195], 0
	v_mfma_f32_16x16x32_bf16 v[12:15], v[128:131], v[200:203], 0
	v_mfma_f32_16x16x32_bf16 v[8:11], v[136:139], v[200:203], 0
	v_mfma_f32_16x16x32_bf16 v[60:63], v[132:135], v[164:167], v[60:63]
	v_mfma_f32_16x16x32_bf16 v[56:59], v[140:143], v[164:167], v[56:59]
	v_mfma_f32_16x16x32_bf16 v[44:47], v[132:135], v[172:175], v[44:47]
	v_mfma_f32_16x16x32_bf16 v[40:43], v[140:143], v[172:175], v[40:43]
	v_mfma_f32_16x16x32_bf16 v[28:31], v[132:135], v[196:199], v[28:31]
	v_mfma_f32_16x16x32_bf16 v[24:27], v[140:143], v[196:199], v[24:27]
	v_mfma_f32_16x16x32_bf16 v[12:15], v[132:135], v[204:207], v[12:15]
	v_mfma_f32_16x16x32_bf16 v[8:11], v[140:143], v[204:207], v[8:11]
	s_setprio 0
	s_setprio 1
	v_mfma_f32_16x16x32_bf16 v[52:55], v[144:147], v[160:163], 0
	v_mfma_f32_16x16x32_bf16 v[48:51], v[152:155], v[160:163], 0
	v_mfma_f32_16x16x32_bf16 v[36:39], v[144:147], v[168:171], 0
	v_mfma_f32_16x16x32_bf16 v[32:35], v[152:155], v[168:171], 0
	v_mfma_f32_16x16x32_bf16 v[20:23], v[144:147], v[192:195], 0
	v_mfma_f32_16x16x32_bf16 v[16:19], v[152:155], v[192:195], 0
	v_mfma_f32_16x16x32_bf16 v[4:7], v[144:147], v[200:203], 0
	v_mfma_f32_16x16x32_bf16 v[0:3], v[152:155], v[200:203], 0
	v_mfma_f32_16x16x32_bf16 v[52:55], v[148:151], v[164:167], v[52:55]
	v_mfma_f32_16x16x32_bf16 v[48:51], v[156:159], v[164:167], v[48:51]
	v_mfma_f32_16x16x32_bf16 v[36:39], v[148:151], v[172:175], v[36:39]
	v_mfma_f32_16x16x32_bf16 v[32:35], v[156:159], v[172:175], v[32:35]
	v_mfma_f32_16x16x32_bf16 v[20:23], v[148:151], v[196:199], v[20:23]
	v_mfma_f32_16x16x32_bf16 v[16:19], v[156:159], v[196:199], v[16:19]
	v_mfma_f32_16x16x32_bf16 v[4:7], v[148:151], v[204:207], v[4:7]
	v_mfma_f32_16x16x32_bf16 v[0:3], v[156:159], v[204:207], v[0:3]
	s_setprio 0
	s_barrier
	s_add_i32 s59, 0, 0x18000
	s_add_i32 s60, 0, 0x1c000
	ds_read_b128 v[128:131], v253
	ds_read_b128 v[132:135], v253 offset:1024
	ds_read_b128 v[136:139], v253 offset:2048
	ds_read_b128 v[140:143], v253 offset:3072
	ds_read_b128 v[144:147], v254
	ds_read_b128 v[148:151], v254 offset:1024
	ds_read_b128 v[152:155], v254 offset:2048
	ds_read_b128 v[156:159], v254 offset:3072
	s_add_u32 s46, s46, 0x80000
	s_addc_u32 s47, s47, 0
	s_mov_b32 m0, s49
	ds_read_b128 v[160:163], v218 offset:32768
	ds_read_b128 v[164:167], v218 offset:33792
	ds_read_b128 v[168:171], v218 offset:34816
	ds_read_b128 v[172:175], v218 offset:35840
	ds_read_b128 v[192:195], v218 offset:36864
	ds_read_b128 v[196:199], v218 offset:37888
	ds_read_b128 v[200:203], v218 offset:38912
	ds_read_b128 v[204:207], v218 offset:39936
	global_load_lds_dwordx4 v176, s[46:47]
	s_mov_b32 m0, s50
	s_nop 0
	global_load_lds_dwordx4 v180, s[46:47]
	s_waitcnt vmcnt(8)
	s_waitcnt lgkmcnt(0)
	s_setprio 1
	s_barrier
	v_mfma_f32_16x16x32_bf16 v[124:127], v[128:131], v[160:163], v[124:127]
	v_mfma_f32_16x16x32_bf16 v[120:123], v[136:139], v[160:163], v[120:123]
	v_mfma_f32_16x16x32_bf16 v[108:111], v[128:131], v[168:171], v[108:111]
	v_mfma_f32_16x16x32_bf16 v[104:107], v[136:139], v[168:171], v[104:107]
	v_mfma_f32_16x16x32_bf16 v[92:95], v[128:131], v[192:195], v[92:95]
	v_mfma_f32_16x16x32_bf16 v[88:91], v[136:139], v[192:195], v[88:91]
	v_mfma_f32_16x16x32_bf16 v[76:79], v[128:131], v[200:203], v[76:79]
	v_mfma_f32_16x16x32_bf16 v[72:75], v[136:139], v[200:203], v[72:75]
	v_mfma_f32_16x16x32_bf16 v[124:127], v[132:135], v[164:167], v[124:127]
	v_mfma_f32_16x16x32_bf16 v[120:123], v[140:143], v[164:167], v[120:123]
	v_mfma_f32_16x16x32_bf16 v[108:111], v[132:135], v[172:175], v[108:111]
	v_mfma_f32_16x16x32_bf16 v[104:107], v[140:143], v[172:175], v[104:107]
	v_mfma_f32_16x16x32_bf16 v[92:95], v[132:135], v[196:199], v[92:95]
	v_mfma_f32_16x16x32_bf16 v[88:91], v[140:143], v[196:199], v[88:91]
	v_mfma_f32_16x16x32_bf16 v[76:79], v[132:135], v[204:207], v[76:79]
	v_mfma_f32_16x16x32_bf16 v[72:75], v[140:143], v[204:207], v[72:75]
	s_setprio 0
	s_setprio 1
	v_mfma_f32_16x16x32_bf16 v[116:119], v[144:147], v[160:163], v[116:119]
	v_mfma_f32_16x16x32_bf16 v[112:115], v[152:155], v[160:163], v[112:115]
	v_mfma_f32_16x16x32_bf16 v[100:103], v[144:147], v[168:171], v[100:103]
	v_mfma_f32_16x16x32_bf16 v[96:99], v[152:155], v[168:171], v[96:99]
	v_mfma_f32_16x16x32_bf16 v[84:87], v[144:147], v[192:195], v[84:87]
	v_mfma_f32_16x16x32_bf16 v[80:83], v[152:155], v[192:195], v[80:83]
	v_mfma_f32_16x16x32_bf16 v[68:71], v[144:147], v[200:203], v[68:71]
	v_mfma_f32_16x16x32_bf16 v[64:67], v[152:155], v[200:203], v[64:67]
	v_mfma_f32_16x16x32_bf16 v[116:119], v[148:151], v[164:167], v[116:119]
	v_mfma_f32_16x16x32_bf16 v[112:115], v[156:159], v[164:167], v[112:115]
	v_mfma_f32_16x16x32_bf16 v[100:103], v[148:151], v[172:175], v[100:103]
	v_mfma_f32_16x16x32_bf16 v[96:99], v[156:159], v[172:175], v[96:99]
	v_mfma_f32_16x16x32_bf16 v[84:87], v[148:151], v[196:199], v[84:87]
	v_mfma_f32_16x16x32_bf16 v[80:83], v[156:159], v[196:199], v[80:83]
	v_mfma_f32_16x16x32_bf16 v[68:71], v[148:151], v[204:207], v[68:71]
	v_mfma_f32_16x16x32_bf16 v[64:67], v[156:159], v[204:207], v[64:67]
	s_setprio 0
	s_barrier
	s_add_i32 s46, s59, s31
	s_mov_b32 m0, s46
	ds_read_b128 v[160:163], v218 offset:49152
	ds_read_b128 v[164:167], v218 offset:50176
	ds_read_b128 v[168:171], v218 offset:51200
	ds_read_b128 v[172:175], v218 offset:52224
	ds_read_b128 v[192:195], v218 offset:53248
	ds_read_b128 v[196:199], v218 offset:54272
	ds_read_b128 v[200:203], v218 offset:55296
	ds_read_b128 v[204:207], v218 offset:56320
	global_load_lds_dwordx4 v178, s[98:99]
	s_add_i32 m0, s46, 0x2000
	s_add_u32 s44, s44, 0x80080
	s_addc_u32 s45, s45, 0
	s_add_i32 s46, s60, s31
	global_load_lds_dwordx4 v182, s[98:99]
	s_mov_b32 m0, s46
	s_nop 0
	global_load_lds_dwordx4 v178, s[44:45]
	s_add_i32 m0, s46, 0x2000
	s_nop 0
	global_load_lds_dwordx4 v182, s[44:45]
	s_mov_b32 m0, s52
	s_nop 0
	global_load_lds_dwordx4 v176, s[100:101]
	s_mov_b32 m0, s53
	s_nop 0
	global_load_lds_dwordx4 v180, s[100:101]
	s_waitcnt vmcnt(8)
	s_waitcnt lgkmcnt(0)
	s_setprio 1
	s_barrier
	v_mfma_f32_16x16x32_bf16 v[60:63], v[128:131], v[160:163], v[60:63]
	v_mfma_f32_16x16x32_bf16 v[56:59], v[136:139], v[160:163], v[56:59]
	v_mfma_f32_16x16x32_bf16 v[44:47], v[128:131], v[168:171], v[44:47]
	v_mfma_f32_16x16x32_bf16 v[40:43], v[136:139], v[168:171], v[40:43]
	v_mfma_f32_16x16x32_bf16 v[28:31], v[128:131], v[192:195], v[28:31]
	v_mfma_f32_16x16x32_bf16 v[24:27], v[136:139], v[192:195], v[24:27]
	v_mfma_f32_16x16x32_bf16 v[12:15], v[128:131], v[200:203], v[12:15]
	v_mfma_f32_16x16x32_bf16 v[8:11], v[136:139], v[200:203], v[8:11]
	v_mfma_f32_16x16x32_bf16 v[60:63], v[132:135], v[164:167], v[60:63]
	v_mfma_f32_16x16x32_bf16 v[56:59], v[140:143], v[164:167], v[56:59]
	v_mfma_f32_16x16x32_bf16 v[44:47], v[132:135], v[172:175], v[44:47]
	v_mfma_f32_16x16x32_bf16 v[40:43], v[140:143], v[172:175], v[40:43]
	v_mfma_f32_16x16x32_bf16 v[28:31], v[132:135], v[196:199], v[28:31]
	v_mfma_f32_16x16x32_bf16 v[24:27], v[140:143], v[196:199], v[24:27]
	v_mfma_f32_16x16x32_bf16 v[12:15], v[132:135], v[204:207], v[12:15]
	v_mfma_f32_16x16x32_bf16 v[8:11], v[140:143], v[204:207], v[8:11]
	s_setprio 0
	s_setprio 1
	v_mfma_f32_16x16x32_bf16 v[52:55], v[144:147], v[160:163], v[52:55]
	v_mfma_f32_16x16x32_bf16 v[48:51], v[152:155], v[160:163], v[48:51]
	v_mfma_f32_16x16x32_bf16 v[36:39], v[144:147], v[168:171], v[36:39]
	v_mfma_f32_16x16x32_bf16 v[32:35], v[152:155], v[168:171], v[32:35]
	v_mfma_f32_16x16x32_bf16 v[20:23], v[144:147], v[192:195], v[20:23]
	v_mfma_f32_16x16x32_bf16 v[16:19], v[152:155], v[192:195], v[16:19]
	v_mfma_f32_16x16x32_bf16 v[4:7], v[144:147], v[200:203], v[4:7]
	v_mfma_f32_16x16x32_bf16 v[0:3], v[152:155], v[200:203], v[0:3]
	v_mfma_f32_16x16x32_bf16 v[52:55], v[148:151], v[164:167], v[52:55]
	v_mfma_f32_16x16x32_bf16 v[48:51], v[156:159], v[164:167], v[48:51]
	v_mfma_f32_16x16x32_bf16 v[36:39], v[148:151], v[172:175], v[36:39]
	v_mfma_f32_16x16x32_bf16 v[32:35], v[156:159], v[172:175], v[32:35]
	v_mfma_f32_16x16x32_bf16 v[20:23], v[148:151], v[196:199], v[20:23]
	v_mfma_f32_16x16x32_bf16 v[16:19], v[156:159], v[196:199], v[16:19]
	v_mfma_f32_16x16x32_bf16 v[4:7], v[148:151], v[204:207], v[4:7]
	v_mfma_f32_16x16x32_bf16 v[0:3], v[156:159], v[204:207], v[0:3]
	s_setprio 0
	s_barrier
	s_add_i32 s58, s58, 2
	s_add_u32 s42, s42, 0x100
	s_addc_u32 s43, s43, 0
	s_add_u32 s25, s25, 0x100
	s_addc_u32 s35, s35, 0
	s_cmp_gt_u32 s58, 29
.LBB0_543:
	ds_read_b128 v[128:131], v216
	ds_read_b128 v[132:135], v216 offset:1024
	ds_read_b128 v[136:139], v216 offset:2048
	ds_read_b128 v[140:143], v216 offset:3072
	ds_read_b128 v[144:147], v217
	ds_read_b128 v[148:151], v217 offset:1024
	ds_read_b128 v[152:155], v217 offset:2048
	ds_read_b128 v[156:159], v217 offset:3072
	s_add_u32 s44, s42, 0xfff80080
	s_addc_u32 s45, s43, -1
	s_cmp_eq_u32 s58, 28
	s_cselect_b32 s47, s0, s45
	s_cselect_b32 s46, s1, s44
	s_cselect_b32 s45, s3, s35
	s_cselect_b32 s44, s9, s25
	s_add_i32 m0, s41, 0xc000
	ds_read_b128 v[160:163], v218
	ds_read_b128 v[164:167], v218 offset:1024
	ds_read_b128 v[168:171], v218 offset:2048
	ds_read_b128 v[172:175], v218 offset:3072
	ds_read_b128 v[192:195], v218 offset:4096
	ds_read_b128 v[196:199], v218 offset:5120
	ds_read_b128 v[200:203], v218 offset:6144
	ds_read_b128 v[204:207], v218 offset:7168
	global_load_lds_dwordx4 v184, s[42:43]
	s_add_i32 m0, s41, 0xe000
	s_nop 0
	global_load_lds_dwordx4 v186, s[42:43]
	s_waitcnt vmcnt(8)
	s_waitcnt lgkmcnt(0)
	s_setprio 1
	s_barrier
	v_mfma_f32_16x16x32_bf16 v[124:127], v[128:131], v[160:163], v[124:127]
	v_mfma_f32_16x16x32_bf16 v[120:123], v[136:139], v[160:163], v[120:123]
	v_mfma_f32_16x16x32_bf16 v[108:111], v[128:131], v[168:171], v[108:111]
	v_mfma_f32_16x16x32_bf16 v[104:107], v[136:139], v[168:171], v[104:107]
	v_mfma_f32_16x16x32_bf16 v[92:95], v[128:131], v[192:195], v[92:95]
	v_mfma_f32_16x16x32_bf16 v[88:91], v[136:139], v[192:195], v[88:91]
	v_mfma_f32_16x16x32_bf16 v[76:79], v[128:131], v[200:203], v[76:79]
	v_mfma_f32_16x16x32_bf16 v[72:75], v[136:139], v[200:203], v[72:75]
	v_mfma_f32_16x16x32_bf16 v[124:127], v[132:135], v[164:167], v[124:127]
	v_mfma_f32_16x16x32_bf16 v[120:123], v[140:143], v[164:167], v[120:123]
	v_mfma_f32_16x16x32_bf16 v[108:111], v[132:135], v[172:175], v[108:111]
	v_mfma_f32_16x16x32_bf16 v[104:107], v[140:143], v[172:175], v[104:107]
	v_mfma_f32_16x16x32_bf16 v[92:95], v[132:135], v[196:199], v[92:95]
	v_mfma_f32_16x16x32_bf16 v[88:91], v[140:143], v[196:199], v[88:91]
	v_mfma_f32_16x16x32_bf16 v[76:79], v[132:135], v[204:207], v[76:79]
	v_mfma_f32_16x16x32_bf16 v[72:75], v[140:143], v[204:207], v[72:75]
	s_setprio 0
	s_setprio 1
	v_mfma_f32_16x16x32_bf16 v[116:119], v[144:147], v[160:163], v[116:119]
	v_mfma_f32_16x16x32_bf16 v[112:115], v[152:155], v[160:163], v[112:115]
	v_mfma_f32_16x16x32_bf16 v[100:103], v[144:147], v[168:171], v[100:103]
	v_mfma_f32_16x16x32_bf16 v[96:99], v[152:155], v[168:171], v[96:99]
	v_mfma_f32_16x16x32_bf16 v[84:87], v[144:147], v[192:195], v[84:87]
	v_mfma_f32_16x16x32_bf16 v[80:83], v[152:155], v[192:195], v[80:83]
	v_mfma_f32_16x16x32_bf16 v[68:71], v[144:147], v[200:203], v[68:71]
	v_mfma_f32_16x16x32_bf16 v[64:67], v[152:155], v[200:203], v[64:67]
	v_mfma_f32_16x16x32_bf16 v[116:119], v[148:151], v[164:167], v[116:119]
	v_mfma_f32_16x16x32_bf16 v[112:115], v[156:159], v[164:167], v[112:115]
	v_mfma_f32_16x16x32_bf16 v[100:103], v[148:151], v[172:175], v[100:103]
	v_mfma_f32_16x16x32_bf16 v[96:99], v[156:159], v[172:175], v[96:99]
	v_mfma_f32_16x16x32_bf16 v[84:87], v[148:151], v[196:199], v[84:87]
	v_mfma_f32_16x16x32_bf16 v[80:83], v[156:159], v[196:199], v[80:83]
	v_mfma_f32_16x16x32_bf16 v[68:71], v[148:151], v[204:207], v[68:71]
	v_mfma_f32_16x16x32_bf16 v[64:67], v[156:159], v[204:207], v[64:67]
	s_setprio 0
	s_barrier
	s_add_i32 s59, s55, s31
	s_add_u32 s98, s44, s20
	s_addc_u32 s99, s45, s21
	s_mov_b32 m0, s59
	ds_read_b128 v[160:163], v218 offset:16384
	ds_read_b128 v[164:167], v218 offset:17408
	ds_read_b128 v[168:171], v218 offset:18432
	ds_read_b128 v[172:175], v218 offset:19456
	ds_read_b128 v[192:195], v218 offset:20480
	ds_read_b128 v[196:199], v218 offset:21504
	ds_read_b128 v[200:203], v218 offset:22528
	ds_read_b128 v[204:207], v218 offset:23552
	global_load_lds_dwordx4 v178, s[44:45]
	s_add_i32 m0, s59, 0x2000
	s_add_u32 s60, s44, 0x80000
	s_addc_u32 s61, s45, 0
	s_add_i32 s59, s56, s31
	global_load_lds_dwordx4 v182, s[44:45]
	s_mov_b32 m0, s59
	s_add_u32 s100, s46, s20
	s_addc_u32 s101, s47, s21
	global_load_lds_dwordx4 v178, s[60:61]
	s_add_i32 m0, s59, 0x2000
	s_nop 0
	global_load_lds_dwordx4 v182, s[60:61]
	s_mov_b32 m0, s41
	s_nop 0
	global_load_lds_dwordx4 v176, s[46:47]
	s_mov_b32 m0, s48
	s_nop 0
	global_load_lds_dwordx4 v180, s[46:47]
	s_waitcnt vmcnt(8)
	s_waitcnt lgkmcnt(0)
	s_setprio 1
	s_barrier
	v_mfma_f32_16x16x32_bf16 v[60:63], v[128:131], v[160:163], v[60:63]
	v_mfma_f32_16x16x32_bf16 v[56:59], v[136:139], v[160:163], v[56:59]
	v_mfma_f32_16x16x32_bf16 v[44:47], v[128:131], v[168:171], v[44:47]
	v_mfma_f32_16x16x32_bf16 v[40:43], v[136:139], v[168:171], v[40:43]
	v_mfma_f32_16x16x32_bf16 v[28:31], v[128:131], v[192:195], v[28:31]
	v_mfma_f32_16x16x32_bf16 v[24:27], v[136:139], v[192:195], v[24:27]
	v_mfma_f32_16x16x32_bf16 v[12:15], v[128:131], v[200:203], v[12:15]
	v_mfma_f32_16x16x32_bf16 v[8:11], v[136:139], v[200:203], v[8:11]
	v_mfma_f32_16x16x32_bf16 v[60:63], v[132:135], v[164:167], v[60:63]
	v_mfma_f32_16x16x32_bf16 v[56:59], v[140:143], v[164:167], v[56:59]
	v_mfma_f32_16x16x32_bf16 v[44:47], v[132:135], v[172:175], v[44:47]
	v_mfma_f32_16x16x32_bf16 v[40:43], v[140:143], v[172:175], v[40:43]
	v_mfma_f32_16x16x32_bf16 v[28:31], v[132:135], v[196:199], v[28:31]
	v_mfma_f32_16x16x32_bf16 v[24:27], v[140:143], v[196:199], v[24:27]
	v_mfma_f32_16x16x32_bf16 v[12:15], v[132:135], v[204:207], v[12:15]
	v_mfma_f32_16x16x32_bf16 v[8:11], v[140:143], v[204:207], v[8:11]
	s_setprio 0
	s_setprio 1
	v_mfma_f32_16x16x32_bf16 v[52:55], v[144:147], v[160:163], v[52:55]
	v_mfma_f32_16x16x32_bf16 v[48:51], v[152:155], v[160:163], v[48:51]
	v_mfma_f32_16x16x32_bf16 v[36:39], v[144:147], v[168:171], v[36:39]
	v_mfma_f32_16x16x32_bf16 v[32:35], v[152:155], v[168:171], v[32:35]
	v_mfma_f32_16x16x32_bf16 v[20:23], v[144:147], v[192:195], v[20:23]
	v_mfma_f32_16x16x32_bf16 v[16:19], v[152:155], v[192:195], v[16:19]
	v_mfma_f32_16x16x32_bf16 v[4:7], v[144:147], v[200:203], v[4:7]
	v_mfma_f32_16x16x32_bf16 v[0:3], v[152:155], v[200:203], v[0:3]
	v_mfma_f32_16x16x32_bf16 v[52:55], v[148:151], v[164:167], v[52:55]
	v_mfma_f32_16x16x32_bf16 v[48:51], v[156:159], v[164:167], v[48:51]
	v_mfma_f32_16x16x32_bf16 v[36:39], v[148:151], v[172:175], v[36:39]
	v_mfma_f32_16x16x32_bf16 v[32:35], v[156:159], v[172:175], v[32:35]
	v_mfma_f32_16x16x32_bf16 v[20:23], v[148:151], v[196:199], v[20:23]
	v_mfma_f32_16x16x32_bf16 v[16:19], v[156:159], v[196:199], v[16:19]
	v_mfma_f32_16x16x32_bf16 v[4:7], v[148:151], v[204:207], v[4:7]
	v_mfma_f32_16x16x32_bf16 v[0:3], v[156:159], v[204:207], v[0:3]
	s_setprio 0
	s_barrier
	s_add_i32 s59, 0, 0x18000
	s_add_i32 s60, 0, 0x1c000
	ds_read_b128 v[128:131], v253
	ds_read_b128 v[132:135], v253 offset:1024
	ds_read_b128 v[136:139], v253 offset:2048
	ds_read_b128 v[140:143], v253 offset:3072
	ds_read_b128 v[144:147], v254
	ds_read_b128 v[148:151], v254 offset:1024
	ds_read_b128 v[152:155], v254 offset:2048
	ds_read_b128 v[156:159], v254 offset:3072
	s_add_u32 s46, s46, 0x80000
	s_addc_u32 s47, s47, 0
	s_mov_b32 m0, s49
	ds_read_b128 v[160:163], v218 offset:32768
	ds_read_b128 v[164:167], v218 offset:33792
	ds_read_b128 v[168:171], v218 offset:34816
	ds_read_b128 v[172:175], v218 offset:35840
	ds_read_b128 v[192:195], v218 offset:36864
	ds_read_b128 v[196:199], v218 offset:37888
	ds_read_b128 v[200:203], v218 offset:38912
	ds_read_b128 v[204:207], v218 offset:39936
	global_load_lds_dwordx4 v176, s[46:47]
	s_mov_b32 m0, s50
	s_nop 0
	global_load_lds_dwordx4 v180, s[46:47]
	s_waitcnt vmcnt(8)
	s_waitcnt lgkmcnt(0)
	s_setprio 1
	s_barrier
	v_mfma_f32_16x16x32_bf16 v[124:127], v[128:131], v[160:163], v[124:127]
	v_mfma_f32_16x16x32_bf16 v[120:123], v[136:139], v[160:163], v[120:123]
	v_mfma_f32_16x16x32_bf16 v[108:111], v[128:131], v[168:171], v[108:111]
	v_mfma_f32_16x16x32_bf16 v[104:107], v[136:139], v[168:171], v[104:107]
	v_mfma_f32_16x16x32_bf16 v[92:95], v[128:131], v[192:195], v[92:95]
	v_mfma_f32_16x16x32_bf16 v[88:91], v[136:139], v[192:195], v[88:91]
	v_mfma_f32_16x16x32_bf16 v[76:79], v[128:131], v[200:203], v[76:79]
	v_mfma_f32_16x16x32_bf16 v[72:75], v[136:139], v[200:203], v[72:75]
	v_mfma_f32_16x16x32_bf16 v[124:127], v[132:135], v[164:167], v[124:127]
	v_mfma_f32_16x16x32_bf16 v[120:123], v[140:143], v[164:167], v[120:123]
	v_mfma_f32_16x16x32_bf16 v[108:111], v[132:135], v[172:175], v[108:111]
	v_mfma_f32_16x16x32_bf16 v[104:107], v[140:143], v[172:175], v[104:107]
	v_mfma_f32_16x16x32_bf16 v[92:95], v[132:135], v[196:199], v[92:95]
	v_mfma_f32_16x16x32_bf16 v[88:91], v[140:143], v[196:199], v[88:91]
	v_mfma_f32_16x16x32_bf16 v[76:79], v[132:135], v[204:207], v[76:79]
	v_mfma_f32_16x16x32_bf16 v[72:75], v[140:143], v[204:207], v[72:75]
	s_setprio 0
	s_setprio 1
	v_mfma_f32_16x16x32_bf16 v[116:119], v[144:147], v[160:163], v[116:119]
	v_mfma_f32_16x16x32_bf16 v[112:115], v[152:155], v[160:163], v[112:115]
	v_mfma_f32_16x16x32_bf16 v[100:103], v[144:147], v[168:171], v[100:103]
	v_mfma_f32_16x16x32_bf16 v[96:99], v[152:155], v[168:171], v[96:99]
	v_mfma_f32_16x16x32_bf16 v[84:87], v[144:147], v[192:195], v[84:87]
	v_mfma_f32_16x16x32_bf16 v[80:83], v[152:155], v[192:195], v[80:83]
	v_mfma_f32_16x16x32_bf16 v[68:71], v[144:147], v[200:203], v[68:71]
	v_mfma_f32_16x16x32_bf16 v[64:67], v[152:155], v[200:203], v[64:67]
	v_mfma_f32_16x16x32_bf16 v[116:119], v[148:151], v[164:167], v[116:119]
	v_mfma_f32_16x16x32_bf16 v[112:115], v[156:159], v[164:167], v[112:115]
	v_mfma_f32_16x16x32_bf16 v[100:103], v[148:151], v[172:175], v[100:103]
	v_mfma_f32_16x16x32_bf16 v[96:99], v[156:159], v[172:175], v[96:99]
	v_mfma_f32_16x16x32_bf16 v[84:87], v[148:151], v[196:199], v[84:87]
	v_mfma_f32_16x16x32_bf16 v[80:83], v[156:159], v[196:199], v[80:83]
	v_mfma_f32_16x16x32_bf16 v[68:71], v[148:151], v[204:207], v[68:71]
	v_mfma_f32_16x16x32_bf16 v[64:67], v[156:159], v[204:207], v[64:67]
	s_setprio 0
	s_barrier
	s_add_i32 s46, s59, s31
	s_mov_b32 m0, s46
	ds_read_b128 v[160:163], v218 offset:49152
	ds_read_b128 v[164:167], v218 offset:50176
	ds_read_b128 v[168:171], v218 offset:51200
	ds_read_b128 v[172:175], v218 offset:52224
	ds_read_b128 v[192:195], v218 offset:53248
	ds_read_b128 v[196:199], v218 offset:54272
	ds_read_b128 v[200:203], v218 offset:55296
	ds_read_b128 v[204:207], v218 offset:56320
	global_load_lds_dwordx4 v178, s[98:99]
	s_add_i32 m0, s46, 0x2000
	s_add_u32 s44, s44, 0x80080
	s_addc_u32 s45, s45, 0
	s_add_i32 s46, s60, s31
	global_load_lds_dwordx4 v182, s[98:99]
	s_mov_b32 m0, s46
	s_nop 0
	global_load_lds_dwordx4 v178, s[44:45]
	s_add_i32 m0, s46, 0x2000
	s_nop 0
	global_load_lds_dwordx4 v182, s[44:45]
	s_mov_b32 m0, s52
	s_nop 0
	global_load_lds_dwordx4 v176, s[100:101]
	s_mov_b32 m0, s53
	s_nop 0
	global_load_lds_dwordx4 v180, s[100:101]
	s_waitcnt vmcnt(8)
	s_waitcnt lgkmcnt(0)
	s_setprio 1
	s_barrier
	v_mfma_f32_16x16x32_bf16 v[60:63], v[128:131], v[160:163], v[60:63]
	v_mfma_f32_16x16x32_bf16 v[56:59], v[136:139], v[160:163], v[56:59]
	v_mfma_f32_16x16x32_bf16 v[44:47], v[128:131], v[168:171], v[44:47]
	v_mfma_f32_16x16x32_bf16 v[40:43], v[136:139], v[168:171], v[40:43]
	v_mfma_f32_16x16x32_bf16 v[28:31], v[128:131], v[192:195], v[28:31]
	v_mfma_f32_16x16x32_bf16 v[24:27], v[136:139], v[192:195], v[24:27]
	v_mfma_f32_16x16x32_bf16 v[12:15], v[128:131], v[200:203], v[12:15]
	v_mfma_f32_16x16x32_bf16 v[8:11], v[136:139], v[200:203], v[8:11]
	v_mfma_f32_16x16x32_bf16 v[60:63], v[132:135], v[164:167], v[60:63]
	v_mfma_f32_16x16x32_bf16 v[56:59], v[140:143], v[164:167], v[56:59]
	v_mfma_f32_16x16x32_bf16 v[44:47], v[132:135], v[172:175], v[44:47]
	v_mfma_f32_16x16x32_bf16 v[40:43], v[140:143], v[172:175], v[40:43]
	v_mfma_f32_16x16x32_bf16 v[28:31], v[132:135], v[196:199], v[28:31]
	v_mfma_f32_16x16x32_bf16 v[24:27], v[140:143], v[196:199], v[24:27]
	v_mfma_f32_16x16x32_bf16 v[12:15], v[132:135], v[204:207], v[12:15]
	v_mfma_f32_16x16x32_bf16 v[8:11], v[140:143], v[204:207], v[8:11]
	s_setprio 0
	s_setprio 1
	v_mfma_f32_16x16x32_bf16 v[52:55], v[144:147], v[160:163], v[52:55]
	v_mfma_f32_16x16x32_bf16 v[48:51], v[152:155], v[160:163], v[48:51]
	v_mfma_f32_16x16x32_bf16 v[36:39], v[144:147], v[168:171], v[36:39]
	v_mfma_f32_16x16x32_bf16 v[32:35], v[152:155], v[168:171], v[32:35]
	v_mfma_f32_16x16x32_bf16 v[20:23], v[144:147], v[192:195], v[20:23]
	v_mfma_f32_16x16x32_bf16 v[16:19], v[152:155], v[192:195], v[16:19]
	v_mfma_f32_16x16x32_bf16 v[4:7], v[144:147], v[200:203], v[4:7]
	v_mfma_f32_16x16x32_bf16 v[0:3], v[152:155], v[200:203], v[0:3]
	v_mfma_f32_16x16x32_bf16 v[52:55], v[148:151], v[164:167], v[52:55]
	v_mfma_f32_16x16x32_bf16 v[48:51], v[156:159], v[164:167], v[48:51]
	v_mfma_f32_16x16x32_bf16 v[36:39], v[148:151], v[172:175], v[36:39]
	v_mfma_f32_16x16x32_bf16 v[32:35], v[156:159], v[172:175], v[32:35]
	v_mfma_f32_16x16x32_bf16 v[20:23], v[148:151], v[196:199], v[20:23]
	v_mfma_f32_16x16x32_bf16 v[16:19], v[156:159], v[196:199], v[16:19]
	v_mfma_f32_16x16x32_bf16 v[4:7], v[148:151], v[204:207], v[4:7]
	v_mfma_f32_16x16x32_bf16 v[0:3], v[156:159], v[204:207], v[0:3]
	s_setprio 0
	s_barrier
	s_add_i32 s58, s58, 2
	s_add_u32 s42, s42, 0x100
	s_addc_u32 s43, s43, 0
	s_add_u32 s25, s25, 0x100
	s_addc_u32 s35, s35, 0
	s_cmp_gt_u32 s58, 29
	s_cbranch_scc0 .LBB0_543
	s_and_b64 vcc, exec, s[22:23]
	s_cbranch_vccz .LBB0_546
	s_barrier

.LBB0_624:
	s_add_u32 s38, s12, 0x6000000
	s_mov_b64 s[40:41], 0x80
	s_addc_u32 s39, s13, 0
	s_add_i32 m0, s72, 0x18000
	v_lshl_add_u64 v[8:9], v[8:9], 0, s[40:41]
	s_lshl_b32 s12, s3, 13
	s_lshl_b32 s79, s1, 5
	s_lshl_b32 s13, s1, 12
	s_waitcnt vmcnt(2)
	s_barrier
	global_load_lds_dwordx4 v[8:9], off
	v_lshl_add_u64 v[6:7], v[6:7], 0, s[40:41]
	s_add_i32 m0, s72, 0x1a000
	s_add_i32 s82, s72, 0x8000
	s_add_i32 s83, s72, 0xa000
	global_load_lds_dwordx4 v[6:7], off
	v_lshl_add_u64 v[4:5], v[4:5], 0, s[40:41]
	s_mov_b32 m0, s82
	s_add_u32 s6, s10, 0x80080
	global_load_lds_dwordx4 v[4:5], off
	v_lshl_add_u64 v[2:3], v[2:3], 0, s[40:41]
	s_mov_b32 m0, s83
	s_addc_u32 s7, s11, 0
	global_load_lds_dwordx4 v[2:3], off
	s_add_i32 m0, s72, 0x1c000
	v_lshl_add_u64 v[2:3], s[6:7], 0, v[154:155]
	global_load_lds_dwordx4 v[2:3], off
	v_lshl_add_u64 v[2:3], s[6:7], 0, v[158:159]
	s_add_i32 m0, s72, 0x1e000
	s_movk_i32 s6, 0x3c0
	global_load_lds_dwordx4 v[2:3], off
	v_lshlrev_b32_e32 v2, 4, v193
	v_lshlrev_b32_e32 v3, 6, v1
	v_lshlrev_b32_e32 v1, 2, v1
	v_and_or_b32 v3, v3, s6, v2
	v_and_b32_e32 v1, 32, v1
	v_bitop3_b32 v3, v3, s12, v1 bitop3:0xde
	v_lshl_or_b32 v1, v192, 6, v2
	v_lshlrev_b32_e32 v2, 2, v192
	v_and_b32_e32 v2, 32, v2
	v_bitop3_b32 v196, v1, s13, v2 bitop3:0xde
	v_add_u32_e32 v253, 0x18000, v196
	v_add_u32_e32 v254, 0x1c000, v196
	s_cmpk_lt_u32 s0, 0x100
	v_mov_b32_e32 v1, v155
	s_cselect_b64 s[42:43], -1, 0
	s_and_b32 s0, s0, 0xffffff00
	s_lshl_b32 s1, s1, 6
	s_lshl_b32 s85, s3, 7
	v_lshl_add_u64 v[160:161], s[4:5], 0, v[0:1]
	v_lshlrev_b32_e32 v0, 15, v10
	s_or_b32 s84, s1, s0
	s_add_i32 s0, s85, 0x100
	v_and_b32_e32 v0, 0xffff0000, v0
	s_cmp_gt_i32 s3, 0
	v_lshl_add_u32 v0, v11, 12, v0
	v_and_b32_e32 v1, 1, v10
	s_cselect_b64 s[44:45], -1, 0
	s_cmp_lt_i32 s3, 3
	v_lshl_or_b32 v0, v1, 6, v0
	s_cselect_b64 s[46:47], -1, 0
	s_lshl_b32 s1, s3, 9
	s_add_i32 s86, s65, 0x80
	v_lshl_add_u32 v162, v12, 1, v0
	v_lshlrev_b32_e32 v0, 15, v13
	s_cmp_gt_i32 s3, -2
	v_and_b32_e32 v0, 0xffff0000, v0
	s_waitcnt vmcnt(6)
	s_cselect_b64 s[48:49], -1, 0
	s_cmp_lt_i32 s3, 1
	v_lshl_add_u32 v0, v14, 12, v0
	v_and_b32_e32 v1, 1, v13
	s_cselect_b64 s[50:51], -1, 0
	s_add_i32 s87, s1, 0x400
	s_add_i32 s89, 0, 0x20000
	s_add_i32 s93, 0, 0x20600
	v_lshl_or_b32 v0, v1, 6, v0
	s_add_i32 s94, 0, 0x10000
	s_add_i32 s95, 0, 0x14000
	s_ashr_i32 s88, s53, 31
	s_add_i32 s90, s89, s1
	s_add_i32 s91, s93, s1
	s_add_i32 s92, s89, s87
	s_add_i32 s93, s93, s87
	v_mov_b32_e32 v163, v155
	v_lshl_add_u32 v164, v15, 1, v0
	v_mov_b32_e32 v165, v155
	v_mov_b64_e32 v[166:167], 0xaeb
	v_mov_b64_e32 v[168:169], 0xaea
	v_add_u32_e32 v197, s94, v196
	v_add_u32_e32 v198, s95, v196
	v_add_u32_e32 v199, 0, v3
	s_add_i32 s96, 0, 0x21400
	v_mov_b32_e32 v200, 0x358637bd
	s_add_i32 s97, 0, 0x20800
	s_lshl_b32 s0, s0, 2
	s_mov_b32 s52, 0x3e6d3388
	s_mov_b32 s54, 0x3f07dc22
	s_mov_b32 s56, 0xbf3a00e3
	s_mov_b32 s58, 0x3f35f0e3
	s_mov_b32 s60, 0xbe11a98e
	s_mov_b32 s62, 0x3e027906
	s_mov_b32 s64, 0xbf38aa3b
	s_movk_i32 s31, 0x2b00
	s_movk_i32 s80, 0x1fff
	s_movk_i32 s81, 0x1ff0
	s_movk_i32 s26, 0x1fe0
	s_movk_i32 s27, 0x1fd0
	s_barrier
	s_branch .LBB0_627

.LBB0_635:
	s_ashr_i32 s67, s66, 31
	s_lshl_b64 s[12:13], s[66:67], 20
	s_add_u32 s70, s55, s12
	s_addc_u32 s71, s57, s13
	s_and_b64 s[6:7], s[6:7], exec
	s_cselect_b32 s1, s71, s11
	s_cselect_b32 s3, s70, s10
	s_add_u32 s6, s8, 0x80080
	s_addc_u32 s7, s9, 0
	s_add_u32 s12, s10, 0x100
	s_addc_u32 s13, s11, 0
	s_mov_b32 s15, -2
	s_waitcnt vmcnt(0)
	ds_read_b128 v[148:151], v197
	ds_read_b128 v[170:173], v197 offset:1024
	ds_read_b128 v[174:177], v197 offset:2048
	ds_read_b128 v[178:181], v197 offset:3072
	ds_read_b128 v[182:185], v198
	ds_read_b128 v[186:189], v198 offset:1024
	ds_read_b128 v[202:205], v198 offset:2048
	ds_read_b128 v[206:209], v198 offset:3072
	s_add_u32 s8, s6, 0xfff80080
	s_addc_u32 s9, s7, -1
	s_cmp_eq_u32 s15, 28
	s_cselect_b32 s11, s69, s9
	s_cselect_b32 s10, s68, s8
	s_cselect_b32 s9, s1, s13
	s_cselect_b32 s8, s3, s12
	s_add_i32 m0, s72, 0xc000
	ds_read_b128 v[214:217], v199
	ds_read_b128 v[218:221], v199 offset:1024
	ds_read_b128 v[222:225], v199 offset:2048
	ds_read_b128 v[226:229], v199 offset:3072
	ds_read_b128 v[230:233], v199 offset:4096
	ds_read_b128 v[234:237], v199 offset:5120
	ds_read_b128 v[238:241], v199 offset:6144
	ds_read_b128 v[242:245], v199 offset:7168
	global_load_lds_dwordx4 v162, s[6:7]
	s_add_i32 m0, s72, 0xe000
	s_nop 0
	global_load_lds_dwordx4 v164, s[6:7]
	s_waitcnt vmcnt(8)
	s_waitcnt lgkmcnt(0)
	s_setprio 1
	s_barrier
	v_mfma_f32_16x16x32_bf16 v[112:115], v[148:151], v[214:217], 0
	v_mfma_f32_16x16x32_bf16 v[80:83], v[174:177], v[214:217], 0
	v_mfma_f32_16x16x32_bf16 v[116:119], v[148:151], v[222:225], 0
	v_mfma_f32_16x16x32_bf16 v[88:91], v[174:177], v[222:225], 0
	v_mfma_f32_16x16x32_bf16 v[124:127], v[148:151], v[230:233], 0
	v_mfma_f32_16x16x32_bf16 v[92:95], v[174:177], v[230:233], 0
	v_mfma_f32_16x16x32_bf16 v[120:123], v[148:151], v[238:241], 0
	v_mfma_f32_16x16x32_bf16 v[84:87], v[174:177], v[238:241], 0
	v_mfma_f32_16x16x32_bf16 v[112:115], v[170:173], v[218:221], v[112:115]
	v_mfma_f32_16x16x32_bf16 v[80:83], v[178:181], v[218:221], v[80:83]
	v_mfma_f32_16x16x32_bf16 v[116:119], v[170:173], v[226:229], v[116:119]
	v_mfma_f32_16x16x32_bf16 v[88:91], v[178:181], v[226:229], v[88:91]
	v_mfma_f32_16x16x32_bf16 v[124:127], v[170:173], v[234:237], v[124:127]
	v_mfma_f32_16x16x32_bf16 v[92:95], v[178:181], v[234:237], v[92:95]
	v_mfma_f32_16x16x32_bf16 v[120:123], v[170:173], v[242:245], v[120:123]
	v_mfma_f32_16x16x32_bf16 v[84:87], v[178:181], v[242:245], v[84:87]
	s_setprio 0
	s_setprio 1
	v_mfma_f32_16x16x32_bf16 v[108:111], v[182:185], v[214:217], 0
	v_mfma_f32_16x16x32_bf16 v[76:79], v[202:205], v[214:217], 0
	v_mfma_f32_16x16x32_bf16 v[104:107], v[182:185], v[222:225], 0
	v_mfma_f32_16x16x32_bf16 v[72:75], v[202:205], v[222:225], 0
	v_mfma_f32_16x16x32_bf16 v[100:103], v[182:185], v[230:233], 0
	v_mfma_f32_16x16x32_bf16 v[68:71], v[202:205], v[230:233], 0
	v_mfma_f32_16x16x32_bf16 v[96:99], v[182:185], v[238:241], 0
	v_mfma_f32_16x16x32_bf16 v[64:67], v[202:205], v[238:241], 0
	v_mfma_f32_16x16x32_bf16 v[108:111], v[186:189], v[218:221], v[108:111]
	v_mfma_f32_16x16x32_bf16 v[76:79], v[206:209], v[218:221], v[76:79]
	v_mfma_f32_16x16x32_bf16 v[104:107], v[186:189], v[226:229], v[104:107]
	v_mfma_f32_16x16x32_bf16 v[72:75], v[206:209], v[226:229], v[72:75]
	v_mfma_f32_16x16x32_bf16 v[100:103], v[186:189], v[234:237], v[100:103]
	v_mfma_f32_16x16x32_bf16 v[68:71], v[206:209], v[234:237], v[68:71]
	v_mfma_f32_16x16x32_bf16 v[96:99], v[186:189], v[242:245], v[96:99]
	v_mfma_f32_16x16x32_bf16 v[64:67], v[206:209], v[242:245], v[64:67]
	s_setprio 0
	s_barrier
	s_add_i32 s16, s94, s63
	s_add_u32 s98, s8, s40
	s_addc_u32 s99, s9, s41
	s_mov_b32 m0, s16
	ds_read_b128 v[214:217], v199 offset:16384
	ds_read_b128 v[218:221], v199 offset:17408
	ds_read_b128 v[222:225], v199 offset:18432
	ds_read_b128 v[226:229], v199 offset:19456
	ds_read_b128 v[230:233], v199 offset:20480
	ds_read_b128 v[234:237], v199 offset:21504
	ds_read_b128 v[238:241], v199 offset:22528
	ds_read_b128 v[242:245], v199 offset:23552
	global_load_lds_dwordx4 v154, s[8:9]
	s_add_i32 m0, s16, 0x2000
	s_add_u32 s16, s8, 0x80000
	s_addc_u32 s17, s9, 0
	s_add_i32 s18, s95, s63
	global_load_lds_dwordx4 v158, s[8:9]
	s_mov_b32 m0, s18
	s_add_u32 s100, s10, s40
	s_addc_u32 s101, s11, s41
	global_load_lds_dwordx4 v154, s[16:17]
	s_add_i32 m0, s18, 0x2000
	s_nop 0
	global_load_lds_dwordx4 v158, s[16:17]
	s_mov_b32 m0, s72
	s_nop 0
	global_load_lds_dwordx4 v152, s[10:11]
	s_mov_b32 m0, s73
	s_nop 0
	global_load_lds_dwordx4 v156, s[10:11]
	s_waitcnt vmcnt(8)
	s_waitcnt lgkmcnt(0)
	s_setprio 1
	s_barrier
	v_mfma_f32_16x16x32_bf16 v[48:51], v[148:151], v[214:217], 0
	v_mfma_f32_16x16x32_bf16 v[16:19], v[174:177], v[214:217], 0
	v_mfma_f32_16x16x32_bf16 v[52:55], v[148:151], v[222:225], 0
	v_mfma_f32_16x16x32_bf16 v[24:27], v[174:177], v[222:225], 0
	v_mfma_f32_16x16x32_bf16 v[60:63], v[148:151], v[230:233], 0
	v_mfma_f32_16x16x32_bf16 v[28:31], v[174:177], v[230:233], 0
	v_mfma_f32_16x16x32_bf16 v[56:59], v[148:151], v[238:241], 0
	v_mfma_f32_16x16x32_bf16 v[20:23], v[174:177], v[238:241], 0
	v_mfma_f32_16x16x32_bf16 v[48:51], v[170:173], v[218:221], v[48:51]
	v_mfma_f32_16x16x32_bf16 v[16:19], v[178:181], v[218:221], v[16:19]
	v_mfma_f32_16x16x32_bf16 v[52:55], v[170:173], v[226:229], v[52:55]
	v_mfma_f32_16x16x32_bf16 v[24:27], v[178:181], v[226:229], v[24:27]
	v_mfma_f32_16x16x32_bf16 v[60:63], v[170:173], v[234:237], v[60:63]
	v_mfma_f32_16x16x32_bf16 v[28:31], v[178:181], v[234:237], v[28:31]
	v_mfma_f32_16x16x32_bf16 v[56:59], v[170:173], v[242:245], v[56:59]
	v_mfma_f32_16x16x32_bf16 v[20:23], v[178:181], v[242:245], v[20:23]
	s_setprio 0
	s_setprio 1
	v_mfma_f32_16x16x32_bf16 v[44:47], v[182:185], v[214:217], 0
	v_mfma_f32_16x16x32_bf16 v[12:15], v[202:205], v[214:217], 0
	v_mfma_f32_16x16x32_bf16 v[40:43], v[182:185], v[222:225], 0
	v_mfma_f32_16x16x32_bf16 v[8:11], v[202:205], v[222:225], 0
	v_mfma_f32_16x16x32_bf16 v[36:39], v[182:185], v[230:233], 0
	v_mfma_f32_16x16x32_bf16 v[4:7], v[202:205], v[230:233], 0
	v_mfma_f32_16x16x32_bf16 v[32:35], v[182:185], v[238:241], 0
	v_mfma_f32_16x16x32_bf16 v[0:3], v[202:205], v[238:241], 0
	v_mfma_f32_16x16x32_bf16 v[44:47], v[186:189], v[218:221], v[44:47]
	v_mfma_f32_16x16x32_bf16 v[12:15], v[206:209], v[218:221], v[12:15]
	v_mfma_f32_16x16x32_bf16 v[40:43], v[186:189], v[226:229], v[40:43]
	v_mfma_f32_16x16x32_bf16 v[8:11], v[206:209], v[226:229], v[8:11]
	v_mfma_f32_16x16x32_bf16 v[36:39], v[186:189], v[234:237], v[36:39]
	v_mfma_f32_16x16x32_bf16 v[4:7], v[206:209], v[234:237], v[4:7]
	v_mfma_f32_16x16x32_bf16 v[32:35], v[186:189], v[242:245], v[32:35]
	v_mfma_f32_16x16x32_bf16 v[0:3], v[206:209], v[242:245], v[0:3]
	s_setprio 0
	s_barrier
	s_add_i32 s16, 0, 0x18000
	s_add_i32 s17, 0, 0x1c000
	ds_read_b128 v[148:151], v253
	ds_read_b128 v[170:173], v253 offset:1024
	ds_read_b128 v[174:177], v253 offset:2048
	ds_read_b128 v[178:181], v253 offset:3072
	ds_read_b128 v[182:185], v254
	ds_read_b128 v[186:189], v254 offset:1024
	ds_read_b128 v[202:205], v254 offset:2048
	ds_read_b128 v[206:209], v254 offset:3072
	s_add_u32 s10, s10, 0x80000
	s_addc_u32 s11, s11, 0
	s_mov_b32 m0, s74
	ds_read_b128 v[214:217], v199 offset:32768
	ds_read_b128 v[218:221], v199 offset:33792
	ds_read_b128 v[222:225], v199 offset:34816
	ds_read_b128 v[226:229], v199 offset:35840
	ds_read_b128 v[230:233], v199 offset:36864
	ds_read_b128 v[234:237], v199 offset:37888
	ds_read_b128 v[238:241], v199 offset:38912
	ds_read_b128 v[242:245], v199 offset:39936
	global_load_lds_dwordx4 v152, s[10:11]
	s_mov_b32 m0, s75
	s_nop 0
	global_load_lds_dwordx4 v156, s[10:11]
	s_waitcnt vmcnt(8)
	s_waitcnt lgkmcnt(0)
	s_setprio 1
	s_barrier
	v_mfma_f32_16x16x32_bf16 v[112:115], v[148:151], v[214:217], v[112:115]
	v_mfma_f32_16x16x32_bf16 v[80:83], v[174:177], v[214:217], v[80:83]
	v_mfma_f32_16x16x32_bf16 v[116:119], v[148:151], v[222:225], v[116:119]
	v_mfma_f32_16x16x32_bf16 v[88:91], v[174:177], v[222:225], v[88:91]
	v_mfma_f32_16x16x32_bf16 v[124:127], v[148:151], v[230:233], v[124:127]
	v_mfma_f32_16x16x32_bf16 v[92:95], v[174:177], v[230:233], v[92:95]
	v_mfma_f32_16x16x32_bf16 v[120:123], v[148:151], v[238:241], v[120:123]
	v_mfma_f32_16x16x32_bf16 v[84:87], v[174:177], v[238:241], v[84:87]
	v_mfma_f32_16x16x32_bf16 v[112:115], v[170:173], v[218:221], v[112:115]
	v_mfma_f32_16x16x32_bf16 v[80:83], v[178:181], v[218:221], v[80:83]
	v_mfma_f32_16x16x32_bf16 v[116:119], v[170:173], v[226:229], v[116:119]
	v_mfma_f32_16x16x32_bf16 v[88:91], v[178:181], v[226:229], v[88:91]
	v_mfma_f32_16x16x32_bf16 v[124:127], v[170:173], v[234:237], v[124:127]
	v_mfma_f32_16x16x32_bf16 v[92:95], v[178:181], v[234:237], v[92:95]
	v_mfma_f32_16x16x32_bf16 v[120:123], v[170:173], v[242:245], v[120:123]
	v_mfma_f32_16x16x32_bf16 v[84:87], v[178:181], v[242:245], v[84:87]
	s_setprio 0
	s_setprio 1
	v_mfma_f32_16x16x32_bf16 v[108:111], v[182:185], v[214:217], v[108:111]
	v_mfma_f32_16x16x32_bf16 v[76:79], v[202:205], v[214:217], v[76:79]
	v_mfma_f32_16x16x32_bf16 v[104:107], v[182:185], v[222:225], v[104:107]
	v_mfma_f32_16x16x32_bf16 v[72:75], v[202:205], v[222:225], v[72:75]
	v_mfma_f32_16x16x32_bf16 v[100:103], v[182:185], v[230:233], v[100:103]
	v_mfma_f32_16x16x32_bf16 v[68:71], v[202:205], v[230:233], v[68:71]
	v_mfma_f32_16x16x32_bf16 v[96:99], v[182:185], v[238:241], v[96:99]
	v_mfma_f32_16x16x32_bf16 v[64:67], v[202:205], v[238:241], v[64:67]
	v_mfma_f32_16x16x32_bf16 v[108:111], v[186:189], v[218:221], v[108:111]
	v_mfma_f32_16x16x32_bf16 v[76:79], v[206:209], v[218:221], v[76:79]
	v_mfma_f32_16x16x32_bf16 v[104:107], v[186:189], v[226:229], v[104:107]
	v_mfma_f32_16x16x32_bf16 v[72:75], v[206:209], v[226:229], v[72:75]
	v_mfma_f32_16x16x32_bf16 v[100:103], v[186:189], v[234:237], v[100:103]
	v_mfma_f32_16x16x32_bf16 v[68:71], v[206:209], v[234:237], v[68:71]
	v_mfma_f32_16x16x32_bf16 v[96:99], v[186:189], v[242:245], v[96:99]
	v_mfma_f32_16x16x32_bf16 v[64:67], v[206:209], v[242:245], v[64:67]
	s_setprio 0
	s_barrier
	s_add_i32 s10, s16, s63
	s_mov_b32 m0, s10
	ds_read_b128 v[214:217], v199 offset:49152
	ds_read_b128 v[218:221], v199 offset:50176
	ds_read_b128 v[222:225], v199 offset:51200
	ds_read_b128 v[226:229], v199 offset:52224
	ds_read_b128 v[230:233], v199 offset:53248
	ds_read_b128 v[234:237], v199 offset:54272
	ds_read_b128 v[238:241], v199 offset:55296
	ds_read_b128 v[242:245], v199 offset:56320
	global_load_lds_dwordx4 v154, s[98:99]
	s_add_i32 m0, s10, 0x2000
	s_add_u32 s8, s8, 0x80080
	s_addc_u32 s9, s9, 0
	s_add_i32 s10, s17, s63
	global_load_lds_dwordx4 v158, s[98:99]
	s_mov_b32 m0, s10
	s_nop 0
	global_load_lds_dwordx4 v154, s[8:9]
	s_add_i32 m0, s10, 0x2000
	s_nop 0
	global_load_lds_dwordx4 v158, s[8:9]
	s_mov_b32 m0, s82
	s_nop 0
	global_load_lds_dwordx4 v152, s[100:101]
	s_mov_b32 m0, s83
	s_nop 0
	global_load_lds_dwordx4 v156, s[100:101]
	s_waitcnt vmcnt(8)
	s_waitcnt lgkmcnt(0)
	s_setprio 1
	s_barrier
	v_mfma_f32_16x16x32_bf16 v[48:51], v[148:151], v[214:217], v[48:51]
	v_mfma_f32_16x16x32_bf16 v[16:19], v[174:177], v[214:217], v[16:19]
	v_mfma_f32_16x16x32_bf16 v[52:55], v[148:151], v[222:225], v[52:55]
	v_mfma_f32_16x16x32_bf16 v[24:27], v[174:177], v[222:225], v[24:27]
	v_mfma_f32_16x16x32_bf16 v[60:63], v[148:151], v[230:233], v[60:63]
	v_mfma_f32_16x16x32_bf16 v[28:31], v[174:177], v[230:233], v[28:31]
	v_mfma_f32_16x16x32_bf16 v[56:59], v[148:151], v[238:241], v[56:59]
	v_mfma_f32_16x16x32_bf16 v[20:23], v[174:177], v[238:241], v[20:23]
	v_mfma_f32_16x16x32_bf16 v[48:51], v[170:173], v[218:221], v[48:51]
	v_mfma_f32_16x16x32_bf16 v[16:19], v[178:181], v[218:221], v[16:19]
	v_mfma_f32_16x16x32_bf16 v[52:55], v[170:173], v[226:229], v[52:55]
	v_mfma_f32_16x16x32_bf16 v[24:27], v[178:181], v[226:229], v[24:27]
	v_mfma_f32_16x16x32_bf16 v[60:63], v[170:173], v[234:237], v[60:63]
	v_mfma_f32_16x16x32_bf16 v[28:31], v[178:181], v[234:237], v[28:31]
	v_mfma_f32_16x16x32_bf16 v[56:59], v[170:173], v[242:245], v[56:59]
	v_mfma_f32_16x16x32_bf16 v[20:23], v[178:181], v[242:245], v[20:23]
	s_setprio 0
	s_setprio 1
	v_mfma_f32_16x16x32_bf16 v[44:47], v[182:185], v[214:217], v[44:47]
	v_mfma_f32_16x16x32_bf16 v[12:15], v[202:205], v[214:217], v[12:15]
	v_mfma_f32_16x16x32_bf16 v[40:43], v[182:185], v[222:225], v[40:43]
	v_mfma_f32_16x16x32_bf16 v[8:11], v[202:205], v[222:225], v[8:11]
	v_mfma_f32_16x16x32_bf16 v[36:39], v[182:185], v[230:233], v[36:39]
	v_mfma_f32_16x16x32_bf16 v[4:7], v[202:205], v[230:233], v[4:7]
	v_mfma_f32_16x16x32_bf16 v[32:35], v[182:185], v[238:241], v[32:35]
	v_mfma_f32_16x16x32_bf16 v[0:3], v[202:205], v[238:241], v[0:3]
	v_mfma_f32_16x16x32_bf16 v[44:47], v[186:189], v[218:221], v[44:47]
	v_mfma_f32_16x16x32_bf16 v[12:15], v[206:209], v[218:221], v[12:15]
	v_mfma_f32_16x16x32_bf16 v[40:43], v[186:189], v[226:229], v[40:43]
	v_mfma_f32_16x16x32_bf16 v[8:11], v[206:209], v[226:229], v[8:11]
	v_mfma_f32_16x16x32_bf16 v[36:39], v[186:189], v[234:237], v[36:39]
	v_mfma_f32_16x16x32_bf16 v[4:7], v[206:209], v[234:237], v[4:7]
	v_mfma_f32_16x16x32_bf16 v[32:35], v[186:189], v[242:245], v[32:35]
	v_mfma_f32_16x16x32_bf16 v[0:3], v[206:209], v[242:245], v[0:3]
	s_setprio 0
	s_barrier
	s_add_i32 s15, s15, 2
	s_add_u32 s6, s6, 0x100
	s_addc_u32 s7, s7, 0
	s_add_u32 s12, s12, 0x100
	s_addc_u32 s13, s13, 0
	s_cmp_gt_u32 s15, 29
.LBB0_636:
	ds_read_b128 v[148:151], v197
	ds_read_b128 v[170:173], v197 offset:1024
	ds_read_b128 v[174:177], v197 offset:2048
	ds_read_b128 v[178:181], v197 offset:3072
	ds_read_b128 v[182:185], v198
	ds_read_b128 v[186:189], v198 offset:1024
	ds_read_b128 v[202:205], v198 offset:2048
	ds_read_b128 v[206:209], v198 offset:3072
	s_add_u32 s8, s6, 0xfff80080
	s_addc_u32 s9, s7, -1
	s_cmp_eq_u32 s15, 28
	s_cselect_b32 s11, s69, s9
	s_cselect_b32 s10, s68, s8
	s_cselect_b32 s9, s1, s13
	s_cselect_b32 s8, s3, s12
	s_add_i32 m0, s72, 0xc000
	ds_read_b128 v[214:217], v199
	ds_read_b128 v[218:221], v199 offset:1024
	ds_read_b128 v[222:225], v199 offset:2048
	ds_read_b128 v[226:229], v199 offset:3072
	ds_read_b128 v[230:233], v199 offset:4096
	ds_read_b128 v[234:237], v199 offset:5120
	ds_read_b128 v[238:241], v199 offset:6144
	ds_read_b128 v[242:245], v199 offset:7168
	global_load_lds_dwordx4 v162, s[6:7]
	s_add_i32 m0, s72, 0xe000
	s_nop 0
	global_load_lds_dwordx4 v164, s[6:7]
	s_waitcnt vmcnt(8)
	s_waitcnt lgkmcnt(0)
	s_setprio 1
	s_barrier
	v_mfma_f32_16x16x32_bf16 v[112:115], v[148:151], v[214:217], v[112:115]
	v_mfma_f32_16x16x32_bf16 v[80:83], v[174:177], v[214:217], v[80:83]
	v_mfma_f32_16x16x32_bf16 v[116:119], v[148:151], v[222:225], v[116:119]
	v_mfma_f32_16x16x32_bf16 v[88:91], v[174:177], v[222:225], v[88:91]
	v_mfma_f32_16x16x32_bf16 v[124:127], v[148:151], v[230:233], v[124:127]
	v_mfma_f32_16x16x32_bf16 v[92:95], v[174:177], v[230:233], v[92:95]
	v_mfma_f32_16x16x32_bf16 v[120:123], v[148:151], v[238:241], v[120:123]
	v_mfma_f32_16x16x32_bf16 v[84:87], v[174:177], v[238:241], v[84:87]
	v_mfma_f32_16x16x32_bf16 v[112:115], v[170:173], v[218:221], v[112:115]
	v_mfma_f32_16x16x32_bf16 v[80:83], v[178:181], v[218:221], v[80:83]
	v_mfma_f32_16x16x32_bf16 v[116:119], v[170:173], v[226:229], v[116:119]
	v_mfma_f32_16x16x32_bf16 v[88:91], v[178:181], v[226:229], v[88:91]
	v_mfma_f32_16x16x32_bf16 v[124:127], v[170:173], v[234:237], v[124:127]
	v_mfma_f32_16x16x32_bf16 v[92:95], v[178:181], v[234:237], v[92:95]
	v_mfma_f32_16x16x32_bf16 v[120:123], v[170:173], v[242:245], v[120:123]
	v_mfma_f32_16x16x32_bf16 v[84:87], v[178:181], v[242:245], v[84:87]
	s_setprio 0
	s_setprio 1
	v_mfma_f32_16x16x32_bf16 v[108:111], v[182:185], v[214:217], v[108:111]
	v_mfma_f32_16x16x32_bf16 v[76:79], v[202:205], v[214:217], v[76:79]
	v_mfma_f32_16x16x32_bf16 v[104:107], v[182:185], v[222:225], v[104:107]
	v_mfma_f32_16x16x32_bf16 v[72:75], v[202:205], v[222:225], v[72:75]
	v_mfma_f32_16x16x32_bf16 v[100:103], v[182:185], v[230:233], v[100:103]
	v_mfma_f32_16x16x32_bf16 v[68:71], v[202:205], v[230:233], v[68:71]
	v_mfma_f32_16x16x32_bf16 v[96:99], v[182:185], v[238:241], v[96:99]
	v_mfma_f32_16x16x32_bf16 v[64:67], v[202:205], v[238:241], v[64:67]
	v_mfma_f32_16x16x32_bf16 v[108:111], v[186:189], v[218:221], v[108:111]
	v_mfma_f32_16x16x32_bf16 v[76:79], v[206:209], v[218:221], v[76:79]
	v_mfma_f32_16x16x32_bf16 v[104:107], v[186:189], v[226:229], v[104:107]
	v_mfma_f32_16x16x32_bf16 v[72:75], v[206:209], v[226:229], v[72:75]
	v_mfma_f32_16x16x32_bf16 v[100:103], v[186:189], v[234:237], v[100:103]
	v_mfma_f32_16x16x32_bf16 v[68:71], v[206:209], v[234:237], v[68:71]
	v_mfma_f32_16x16x32_bf16 v[96:99], v[186:189], v[242:245], v[96:99]
	v_mfma_f32_16x16x32_bf16 v[64:67], v[206:209], v[242:245], v[64:67]
	s_setprio 0
	s_barrier
	s_add_i32 s16, s94, s63
	s_add_u32 s98, s8, s40
	s_addc_u32 s99, s9, s41
	s_mov_b32 m0, s16
	ds_read_b128 v[214:217], v199 offset:16384
	ds_read_b128 v[218:221], v199 offset:17408
	ds_read_b128 v[222:225], v199 offset:18432
	ds_read_b128 v[226:229], v199 offset:19456
	ds_read_b128 v[230:233], v199 offset:20480
	ds_read_b128 v[234:237], v199 offset:21504
	ds_read_b128 v[238:241], v199 offset:22528
	ds_read_b128 v[242:245], v199 offset:23552
	global_load_lds_dwordx4 v154, s[8:9]
	s_add_i32 m0, s16, 0x2000
	s_add_u32 s16, s8, 0x80000
	s_addc_u32 s17, s9, 0
	s_add_i32 s18, s95, s63
	global_load_lds_dwordx4 v158, s[8:9]
	s_mov_b32 m0, s18
	s_add_u32 s100, s10, s40
	s_addc_u32 s101, s11, s41
	global_load_lds_dwordx4 v154, s[16:17]
	s_add_i32 m0, s18, 0x2000
	s_nop 0
	global_load_lds_dwordx4 v158, s[16:17]
	s_mov_b32 m0, s72
	s_nop 0
	global_load_lds_dwordx4 v152, s[10:11]
	s_mov_b32 m0, s73
	s_nop 0
	global_load_lds_dwordx4 v156, s[10:11]
	s_waitcnt vmcnt(8)
	s_waitcnt lgkmcnt(0)
	s_setprio 1
	s_barrier
	v_mfma_f32_16x16x32_bf16 v[48:51], v[148:151], v[214:217], v[48:51]
	v_mfma_f32_16x16x32_bf16 v[16:19], v[174:177], v[214:217], v[16:19]
	v_mfma_f32_16x16x32_bf16 v[52:55], v[148:151], v[222:225], v[52:55]
	v_mfma_f32_16x16x32_bf16 v[24:27], v[174:177], v[222:225], v[24:27]
	v_mfma_f32_16x16x32_bf16 v[60:63], v[148:151], v[230:233], v[60:63]
	v_mfma_f32_16x16x32_bf16 v[28:31], v[174:177], v[230:233], v[28:31]
	v_mfma_f32_16x16x32_bf16 v[56:59], v[148:151], v[238:241], v[56:59]
	v_mfma_f32_16x16x32_bf16 v[20:23], v[174:177], v[238:241], v[20:23]
	v_mfma_f32_16x16x32_bf16 v[48:51], v[170:173], v[218:221], v[48:51]
	v_mfma_f32_16x16x32_bf16 v[16:19], v[178:181], v[218:221], v[16:19]
	v_mfma_f32_16x16x32_bf16 v[52:55], v[170:173], v[226:229], v[52:55]
	v_mfma_f32_16x16x32_bf16 v[24:27], v[178:181], v[226:229], v[24:27]
	v_mfma_f32_16x16x32_bf16 v[60:63], v[170:173], v[234:237], v[60:63]
	v_mfma_f32_16x16x32_bf16 v[28:31], v[178:181], v[234:237], v[28:31]
	v_mfma_f32_16x16x32_bf16 v[56:59], v[170:173], v[242:245], v[56:59]
	v_mfma_f32_16x16x32_bf16 v[20:23], v[178:181], v[242:245], v[20:23]
	s_setprio 0
	s_setprio 1
	v_mfma_f32_16x16x32_bf16 v[44:47], v[182:185], v[214:217], v[44:47]
	v_mfma_f32_16x16x32_bf16 v[12:15], v[202:205], v[214:217], v[12:15]
	v_mfma_f32_16x16x32_bf16 v[40:43], v[182:185], v[222:225], v[40:43]
	v_mfma_f32_16x16x32_bf16 v[8:11], v[202:205], v[222:225], v[8:11]
	v_mfma_f32_16x16x32_bf16 v[36:39], v[182:185], v[230:233], v[36:39]
	v_mfma_f32_16x16x32_bf16 v[4:7], v[202:205], v[230:233], v[4:7]
	v_mfma_f32_16x16x32_bf16 v[32:35], v[182:185], v[238:241], v[32:35]
	v_mfma_f32_16x16x32_bf16 v[0:3], v[202:205], v[238:241], v[0:3]
	v_mfma_f32_16x16x32_bf16 v[44:47], v[186:189], v[218:221], v[44:47]
	v_mfma_f32_16x16x32_bf16 v[12:15], v[206:209], v[218:221], v[12:15]
	v_mfma_f32_16x16x32_bf16 v[40:43], v[186:189], v[226:229], v[40:43]
	v_mfma_f32_16x16x32_bf16 v[8:11], v[206:209], v[226:229], v[8:11]
	v_mfma_f32_16x16x32_bf16 v[36:39], v[186:189], v[234:237], v[36:39]
	v_mfma_f32_16x16x32_bf16 v[4:7], v[206:209], v[234:237], v[4:7]
	v_mfma_f32_16x16x32_bf16 v[32:35], v[186:189], v[242:245], v[32:35]
	v_mfma_f32_16x16x32_bf16 v[0:3], v[206:209], v[242:245], v[0:3]
	s_setprio 0
	s_barrier
	s_add_i32 s16, 0, 0x18000
	s_add_i32 s17, 0, 0x1c000
	ds_read_b128 v[148:151], v253
	ds_read_b128 v[170:173], v253 offset:1024
	ds_read_b128 v[174:177], v253 offset:2048
	ds_read_b128 v[178:181], v253 offset:3072
	ds_read_b128 v[182:185], v254
	ds_read_b128 v[186:189], v254 offset:1024
	ds_read_b128 v[202:205], v254 offset:2048
	ds_read_b128 v[206:209], v254 offset:3072
	s_add_u32 s10, s10, 0x80000
	s_addc_u32 s11, s11, 0
	s_mov_b32 m0, s74
	ds_read_b128 v[214:217], v199 offset:32768
	ds_read_b128 v[218:221], v199 offset:33792
	ds_read_b128 v[222:225], v199 offset:34816
	ds_read_b128 v[226:229], v199 offset:35840
	ds_read_b128 v[230:233], v199 offset:36864
	ds_read_b128 v[234:237], v199 offset:37888
	ds_read_b128 v[238:241], v199 offset:38912
	ds_read_b128 v[242:245], v199 offset:39936
	global_load_lds_dwordx4 v152, s[10:11]
	s_mov_b32 m0, s75
	s_nop 0
	global_load_lds_dwordx4 v156, s[10:11]
	s_waitcnt vmcnt(8)
	s_waitcnt lgkmcnt(0)
	s_setprio 1
	s_barrier
	v_mfma_f32_16x16x32_bf16 v[112:115], v[148:151], v[214:217], v[112:115]
	v_mfma_f32_16x16x32_bf16 v[80:83], v[174:177], v[214:217], v[80:83]
	v_mfma_f32_16x16x32_bf16 v[116:119], v[148:151], v[222:225], v[116:119]
	v_mfma_f32_16x16x32_bf16 v[88:91], v[174:177], v[222:225], v[88:91]
	v_mfma_f32_16x16x32_bf16 v[124:127], v[148:151], v[230:233], v[124:127]
	v_mfma_f32_16x16x32_bf16 v[92:95], v[174:177], v[230:233], v[92:95]
	v_mfma_f32_16x16x32_bf16 v[120:123], v[148:151], v[238:241], v[120:123]
	v_mfma_f32_16x16x32_bf16 v[84:87], v[174:177], v[238:241], v[84:87]
	v_mfma_f32_16x16x32_bf16 v[112:115], v[170:173], v[218:221], v[112:115]
	v_mfma_f32_16x16x32_bf16 v[80:83], v[178:181], v[218:221], v[80:83]
	v_mfma_f32_16x16x32_bf16 v[116:119], v[170:173], v[226:229], v[116:119]
	v_mfma_f32_16x16x32_bf16 v[88:91], v[178:181], v[226:229], v[88:91]
	v_mfma_f32_16x16x32_bf16 v[124:127], v[170:173], v[234:237], v[124:127]
	v_mfma_f32_16x16x32_bf16 v[92:95], v[178:181], v[234:237], v[92:95]
	v_mfma_f32_16x16x32_bf16 v[120:123], v[170:173], v[242:245], v[120:123]
	v_mfma_f32_16x16x32_bf16 v[84:87], v[178:181], v[242:245], v[84:87]
	s_setprio 0
	s_setprio 1
	v_mfma_f32_16x16x32_bf16 v[108:111], v[182:185], v[214:217], v[108:111]
	v_mfma_f32_16x16x32_bf16 v[76:79], v[202:205], v[214:217], v[76:79]
	v_mfma_f32_16x16x32_bf16 v[104:107], v[182:185], v[222:225], v[104:107]
	v_mfma_f32_16x16x32_bf16 v[72:75], v[202:205], v[222:225], v[72:75]
	v_mfma_f32_16x16x32_bf16 v[100:103], v[182:185], v[230:233], v[100:103]
	v_mfma_f32_16x16x32_bf16 v[68:71], v[202:205], v[230:233], v[68:71]
	v_mfma_f32_16x16x32_bf16 v[96:99], v[182:185], v[238:241], v[96:99]
	v_mfma_f32_16x16x32_bf16 v[64:67], v[202:205], v[238:241], v[64:67]
	v_mfma_f32_16x16x32_bf16 v[108:111], v[186:189], v[218:221], v[108:111]
	v_mfma_f32_16x16x32_bf16 v[76:79], v[206:209], v[218:221], v[76:79]
	v_mfma_f32_16x16x32_bf16 v[104:107], v[186:189], v[226:229], v[104:107]
	v_mfma_f32_16x16x32_bf16 v[72:75], v[206:209], v[226:229], v[72:75]
	v_mfma_f32_16x16x32_bf16 v[100:103], v[186:189], v[234:237], v[100:103]
	v_mfma_f32_16x16x32_bf16 v[68:71], v[206:209], v[234:237], v[68:71]
	v_mfma_f32_16x16x32_bf16 v[96:99], v[186:189], v[242:245], v[96:99]
	v_mfma_f32_16x16x32_bf16 v[64:67], v[206:209], v[242:245], v[64:67]
	s_setprio 0
	s_barrier
	s_add_i32 s10, s16, s63
	s_mov_b32 m0, s10
	ds_read_b128 v[214:217], v199 offset:49152
	ds_read_b128 v[218:221], v199 offset:50176
	ds_read_b128 v[222:225], v199 offset:51200
	ds_read_b128 v[226:229], v199 offset:52224
	ds_read_b128 v[230:233], v199 offset:53248
	ds_read_b128 v[234:237], v199 offset:54272
	ds_read_b128 v[238:241], v199 offset:55296
	ds_read_b128 v[242:245], v199 offset:56320
	global_load_lds_dwordx4 v154, s[98:99]
	s_add_i32 m0, s10, 0x2000
	s_add_u32 s8, s8, 0x80080
	s_addc_u32 s9, s9, 0
	s_add_i32 s10, s17, s63
	global_load_lds_dwordx4 v158, s[98:99]
	s_mov_b32 m0, s10
	s_nop 0
	global_load_lds_dwordx4 v154, s[8:9]
	s_add_i32 m0, s10, 0x2000
	s_nop 0
	global_load_lds_dwordx4 v158, s[8:9]
	s_mov_b32 m0, s82
	s_nop 0
	global_load_lds_dwordx4 v152, s[100:101]
	s_mov_b32 m0, s83
	s_nop 0
	global_load_lds_dwordx4 v156, s[100:101]
	s_waitcnt vmcnt(8)
	s_waitcnt lgkmcnt(0)
	s_setprio 1
	s_barrier
	v_mfma_f32_16x16x32_bf16 v[48:51], v[148:151], v[214:217], v[48:51]
	v_mfma_f32_16x16x32_bf16 v[16:19], v[174:177], v[214:217], v[16:19]
	v_mfma_f32_16x16x32_bf16 v[52:55], v[148:151], v[222:225], v[52:55]
	v_mfma_f32_16x16x32_bf16 v[24:27], v[174:177], v[222:225], v[24:27]
	v_mfma_f32_16x16x32_bf16 v[60:63], v[148:151], v[230:233], v[60:63]
	v_mfma_f32_16x16x32_bf16 v[28:31], v[174:177], v[230:233], v[28:31]
	v_mfma_f32_16x16x32_bf16 v[56:59], v[148:151], v[238:241], v[56:59]
	v_mfma_f32_16x16x32_bf16 v[20:23], v[174:177], v[238:241], v[20:23]
	v_mfma_f32_16x16x32_bf16 v[48:51], v[170:173], v[218:221], v[48:51]
	v_mfma_f32_16x16x32_bf16 v[16:19], v[178:181], v[218:221], v[16:19]
	v_mfma_f32_16x16x32_bf16 v[52:55], v[170:173], v[226:229], v[52:55]
	v_mfma_f32_16x16x32_bf16 v[24:27], v[178:181], v[226:229], v[24:27]
	v_mfma_f32_16x16x32_bf16 v[60:63], v[170:173], v[234:237], v[60:63]
	v_mfma_f32_16x16x32_bf16 v[28:31], v[178:181], v[234:237], v[28:31]
	v_mfma_f32_16x16x32_bf16 v[56:59], v[170:173], v[242:245], v[56:59]
	v_mfma_f32_16x16x32_bf16 v[20:23], v[178:181], v[242:245], v[20:23]
	s_setprio 0
	s_setprio 1
	v_mfma_f32_16x16x32_bf16 v[44:47], v[182:185], v[214:217], v[44:47]
	v_mfma_f32_16x16x32_bf16 v[12:15], v[202:205], v[214:217], v[12:15]
	v_mfma_f32_16x16x32_bf16 v[40:43], v[182:185], v[222:225], v[40:43]
	v_mfma_f32_16x16x32_bf16 v[8:11], v[202:205], v[222:225], v[8:11]
	v_mfma_f32_16x16x32_bf16 v[36:39], v[182:185], v[230:233], v[36:39]
	v_mfma_f32_16x16x32_bf16 v[4:7], v[202:205], v[230:233], v[4:7]
	v_mfma_f32_16x16x32_bf16 v[32:35], v[182:185], v[238:241], v[32:35]
	v_mfma_f32_16x16x32_bf16 v[0:3], v[202:205], v[238:241], v[0:3]
	v_mfma_f32_16x16x32_bf16 v[44:47], v[186:189], v[218:221], v[44:47]
	v_mfma_f32_16x16x32_bf16 v[12:15], v[206:209], v[218:221], v[12:15]
	v_mfma_f32_16x16x32_bf16 v[40:43], v[186:189], v[226:229], v[40:43]
	v_mfma_f32_16x16x32_bf16 v[8:11], v[206:209], v[226:229], v[8:11]
	v_mfma_f32_16x16x32_bf16 v[36:39], v[186:189], v[234:237], v[36:39]
	v_mfma_f32_16x16x32_bf16 v[4:7], v[206:209], v[234:237], v[4:7]
	v_mfma_f32_16x16x32_bf16 v[32:35], v[186:189], v[242:245], v[32:35]
	v_mfma_f32_16x16x32_bf16 v[0:3], v[206:209], v[242:245], v[0:3]
	s_setprio 0
	s_barrier
	s_add_i32 s15, s15, 2
	s_add_u32 s6, s6, 0x100
	s_addc_u32 s7, s7, 0
	s_add_u32 s12, s12, 0x100
	s_addc_u32 s13, s13, 0
	s_cmp_gt_u32 s15, 29
	s_cbranch_scc0 .LBB0_636
	s_and_b64 vcc, exec, s[42:43]
	s_cbranch_vccz .LBB0_639
	s_barrier

.LBB0_870:
	s_add_u32 s20, s8, 0x180000
	s_addc_u32 s21, s9, 0
	s_add_u32 s53, s8, 0x8000
	s_mov_b64 s[24:25], 0x80
	s_addc_u32 s54, s9, 0
	s_and_b32 s5, s5, 3
	s_add_i32 m0, s48, 0x18000
	v_lshl_add_u64 v[6:7], v[6:7], 0, s[24:25]
	s_lshl_b32 s55, s7, 6
	s_lshl_b32 s30, s7, 13
	s_lshl_b32 s31, s5, 12
	s_lshl_b32 s36, s5, 5
	s_waitcnt vmcnt(2)
	s_barrier
	global_load_lds_dwordx4 v[6:7], off
	v_lshl_add_u64 v[4:5], v[4:5], 0, s[24:25]
	s_add_i32 m0, s48, 0x1a000
	s_add_i32 s56, s48, 0x8000
	s_add_i32 s57, s48, 0xa000
	global_load_lds_dwordx4 v[4:5], off
	v_lshl_add_u64 v[0:1], v[0:1], 0, s[24:25]
	s_mov_b32 m0, s56
	s_add_u32 s26, s16, 0x158080
	global_load_lds_dwordx4 v[0:1], off
	v_lshl_add_u64 v[0:1], v[2:3], 0, s[24:25]
	s_mov_b32 m0, s57
	s_addc_u32 s27, s17, 0
	global_load_lds_dwordx4 v[0:1], off
	s_add_i32 m0, s48, 0x1c000
	v_lshl_add_u64 v[0:1], s[26:27], 0, v[154:155]
	global_load_lds_dwordx4 v[0:1], off
	v_lshl_add_u64 v[0:1], s[26:27], 0, v[158:159]
	s_add_i32 m0, s48, 0x1e000
	s_cmpk_lt_u32 s1, 0x100
	global_load_lds_dwordx4 v[0:1], off
	s_cselect_b64 s[26:27], -1, 0
	s_lshl_b32 s1, s7, 2
	v_bfe_u32 v186, v180, 4, 2
	s_or_b32 s1, s1, s5
	v_and_b32_e32 v185, 15, v180
	v_lshlrev_b32_e32 v0, 4, v186
	v_lshlrev_b32_e32 v1, 2, v180
	s_lshl_b32 s59, s1, 6
	v_lshl_or_b32 v0, v185, 6, v0
	v_and_b32_e32 v1, 32, v1
	s_cmp_eq_u32 s1, 0
	v_bitop3_b32 v2, v0, s30, v1 bitop3:0xde
	v_bitop3_b32 v187, v0, s31, v1 bitop3:0xde
	v_add_u32_e32 v253, 0x18000, v187
	v_add_u32_e32 v254, 0x1c000, v187
	s_cselect_b64 s[30:31], -1, 0
	s_lshl_b32 s1, s5, 2
	s_add_i32 s67, s1, 0
	s_lshl_b32 s1, s46, 8
	s_or_b32 s69, s36, s1
	v_lshrrev_b32_e32 v1, 1, v8
	v_mul_lo_u32 v0, v10, s3
	s_mov_b32 s1, 0x15800
	s_or_b32 s68, s6, 1
	v_mad_u64_u32 v[0:1], s[6:7], v1, s1, v[0:1]
	v_or_b32_e32 v0, v0, v9
	s_mov_b64 s[34:35], 0x158080
	v_add_lshl_u32 v0, v0, v11, 1
	v_mov_b32_e32 v1, v155
	s_add_i32 s60, s67, 0x20000
	s_add_i32 s61, s67, 0x20100
	s_add_i32 s62, s67, 0x20200
	s_add_i32 s63, s67, 0x20300
	s_add_i32 s64, s67, 0x20800
	s_add_i32 s65, s67, 0x20900
	s_add_i32 s66, s67, 0x20a00
	s_add_i32 s67, s67, 0x20b00
	v_lshl_add_u64 v[160:161], v[0:1], 0, s[34:35]
	v_lshrrev_b32_e32 v1, 1, v12
	v_mul_lo_u32 v0, v13, s3
	v_mad_u64_u32 v[0:1], s[6:7], v1, s1, v[0:1]
	s_add_u32 s1, s22, s4
	v_or_b32_e32 v0, v0, v14
	s_addc_u32 s3, s23, 0
	s_waitcnt vmcnt(6)
	v_add_lshl_u32 v0, v0, v15, 1
	v_mov_b32_e32 v1, v155
	s_add_u32 s22, s1, 0x4900100
	v_lshl_add_u64 v[162:163], v[0:1], 0, s[34:35]
	s_addc_u32 s23, s3, 0
	s_add_i32 s70, 0, 0x10000
	s_add_i32 s71, 0, 0x14000
	v_mbcnt_lo_u32_b32 v0, -1, 0
	s_movk_i32 s58, 0x100
	s_mov_b64 s[4:5], -1
	v_add_u32_e32 v188, s70, v187
	v_add_u32_e32 v189, s71, v187
	v_add_u32_e32 v190, 0, v2
	v_mbcnt_hi_u32_b32 v191, -1, v0
	s_mov_b64 s[34:35], 0x80000
	v_mov_b32_e32 v192, 0x358637bd
	s_mov_b32 s72, 0xf800000
	v_mov_b32_e32 v193, 0x260
	v_mov_b64_e32 v[164:165], 0x1e8481
	s_mov_b64 s[36:37], s[38:39]
	s_barrier
	s_branch .LBB0_873

.LBB0_875:
	s_mov_b32 s1, -2
	s_mov_b64 s[4:5], s[22:23]
	ds_read_b128 v[128:131], v188
	ds_read_b128 v[132:135], v188 offset:1024
	ds_read_b128 v[136:139], v188 offset:2048
	ds_read_b128 v[140:143], v188 offset:3072
	ds_read_b128 v[144:147], v189
	ds_read_b128 v[148:151], v189 offset:1024
	ds_read_b128 v[166:169], v189 offset:2048
	ds_read_b128 v[170:173], v189 offset:3072
	s_add_u32 s40, s38, 0x100
	s_addc_u32 s41, s39, 0
	s_cmpk_eq_i32 s1, 0x52
	s_cselect_b32 s45, s37, s41
	s_cselect_b32 s44, s36, s40
	s_cselect_b32 s43, s17, s5
	s_cselect_b32 s42, s16, s4
	s_add_i32 m0, s48, 0xc000
	ds_read_b128 v[174:177], v190
	ds_read_b128 v[178:181], v190 offset:1024
	ds_read_b128 v[194:197], v190 offset:2048
	ds_read_b128 v[198:201], v190 offset:3072
	ds_read_b128 v[202:205], v190 offset:4096
	ds_read_b128 v[206:209], v190 offset:5120
	ds_read_b128 v[210:213], v190 offset:6144
	ds_read_b128 v[214:217], v190 offset:7168
	global_load_lds_dwordx4 v160, s[38:39]
	s_add_i32 m0, s48, 0xe000
	s_nop 0
	global_load_lds_dwordx4 v162, s[38:39]
	s_waitcnt vmcnt(8)
	s_waitcnt lgkmcnt(0)
	s_setprio 1
	s_barrier
	v_mfma_f32_16x16x32_bf16 v[124:127], v[128:131], v[174:177], 0
	v_mfma_f32_16x16x32_bf16 v[120:123], v[136:139], v[174:177], 0
	v_mfma_f32_16x16x32_bf16 v[108:111], v[128:131], v[194:197], 0
	v_mfma_f32_16x16x32_bf16 v[104:107], v[136:139], v[194:197], 0
	v_mfma_f32_16x16x32_bf16 v[92:95], v[128:131], v[202:205], 0
	v_mfma_f32_16x16x32_bf16 v[88:91], v[136:139], v[202:205], 0
	v_mfma_f32_16x16x32_bf16 v[76:79], v[128:131], v[210:213], 0
	v_mfma_f32_16x16x32_bf16 v[72:75], v[136:139], v[210:213], 0
	v_mfma_f32_16x16x32_bf16 v[124:127], v[132:135], v[178:181], v[124:127]
	v_mfma_f32_16x16x32_bf16 v[120:123], v[140:143], v[178:181], v[120:123]
	v_mfma_f32_16x16x32_bf16 v[108:111], v[132:135], v[198:201], v[108:111]
	v_mfma_f32_16x16x32_bf16 v[104:107], v[140:143], v[198:201], v[104:107]
	v_mfma_f32_16x16x32_bf16 v[92:95], v[132:135], v[206:209], v[92:95]
	v_mfma_f32_16x16x32_bf16 v[88:91], v[140:143], v[206:209], v[88:91]
	v_mfma_f32_16x16x32_bf16 v[76:79], v[132:135], v[214:217], v[76:79]
	v_mfma_f32_16x16x32_bf16 v[72:75], v[140:143], v[214:217], v[72:75]
	s_setprio 0
	s_setprio 1
	v_mfma_f32_16x16x32_bf16 v[116:119], v[144:147], v[174:177], 0
	v_mfma_f32_16x16x32_bf16 v[112:115], v[166:169], v[174:177], 0
	v_mfma_f32_16x16x32_bf16 v[100:103], v[144:147], v[194:197], 0
	v_mfma_f32_16x16x32_bf16 v[96:99], v[166:169], v[194:197], 0
	v_mfma_f32_16x16x32_bf16 v[84:87], v[144:147], v[202:205], 0
	v_mfma_f32_16x16x32_bf16 v[80:83], v[166:169], v[202:205], 0
	v_mfma_f32_16x16x32_bf16 v[68:71], v[144:147], v[210:213], 0
	v_mfma_f32_16x16x32_bf16 v[64:67], v[166:169], v[210:213], 0
	v_mfma_f32_16x16x32_bf16 v[116:119], v[148:151], v[178:181], v[116:119]
	v_mfma_f32_16x16x32_bf16 v[112:115], v[170:173], v[178:181], v[112:115]
	v_mfma_f32_16x16x32_bf16 v[100:103], v[148:151], v[198:201], v[100:103]
	v_mfma_f32_16x16x32_bf16 v[96:99], v[170:173], v[198:201], v[96:99]
	v_mfma_f32_16x16x32_bf16 v[84:87], v[148:151], v[206:209], v[84:87]
	v_mfma_f32_16x16x32_bf16 v[80:83], v[170:173], v[206:209], v[80:83]
	v_mfma_f32_16x16x32_bf16 v[68:71], v[148:151], v[214:217], v[68:71]
	v_mfma_f32_16x16x32_bf16 v[64:67], v[170:173], v[214:217], v[64:67]
	s_setprio 0
	s_barrier
	s_add_i32 s3, s70, s33
	s_add_u32 s98, s42, s24
	s_addc_u32 s99, s43, s25
	s_mov_b32 m0, s3
	ds_read_b128 v[174:177], v190 offset:16384
	ds_read_b128 v[178:181], v190 offset:17408
	ds_read_b128 v[194:197], v190 offset:18432
	ds_read_b128 v[198:201], v190 offset:19456
	ds_read_b128 v[202:205], v190 offset:20480
	ds_read_b128 v[206:209], v190 offset:21504
	ds_read_b128 v[210:213], v190 offset:22528
	ds_read_b128 v[214:217], v190 offset:23552
	global_load_lds_dwordx4 v154, s[42:43]
	s_add_i32 m0, s3, 0x2000
	s_add_u32 s38, s42, 0x158000
	s_addc_u32 s39, s43, 0
	s_add_i32 s3, s71, s33
	global_load_lds_dwordx4 v158, s[42:43]
	s_mov_b32 m0, s3
	s_add_u32 s100, s44, s24
	s_addc_u32 s101, s45, s25
	global_load_lds_dwordx4 v154, s[38:39]
	s_add_i32 m0, s3, 0x2000
	s_nop 0
	global_load_lds_dwordx4 v158, s[38:39]
	s_mov_b32 m0, s48
	s_nop 0
	global_load_lds_dwordx4 v152, s[44:45]
	s_mov_b32 m0, s49
	s_nop 0
	global_load_lds_dwordx4 v156, s[44:45]
	s_waitcnt vmcnt(8)
	s_waitcnt lgkmcnt(0)
	s_setprio 1
	s_barrier
	v_mfma_f32_16x16x32_bf16 v[60:63], v[128:131], v[174:177], 0
	v_mfma_f32_16x16x32_bf16 v[56:59], v[136:139], v[174:177], 0
	v_mfma_f32_16x16x32_bf16 v[44:47], v[128:131], v[194:197], 0
	v_mfma_f32_16x16x32_bf16 v[40:43], v[136:139], v[194:197], 0
	v_mfma_f32_16x16x32_bf16 v[28:31], v[128:131], v[202:205], 0
	v_mfma_f32_16x16x32_bf16 v[24:27], v[136:139], v[202:205], 0
	v_mfma_f32_16x16x32_bf16 v[12:15], v[128:131], v[210:213], 0
	v_mfma_f32_16x16x32_bf16 v[8:11], v[136:139], v[210:213], 0
	v_mfma_f32_16x16x32_bf16 v[60:63], v[132:135], v[178:181], v[60:63]
	v_mfma_f32_16x16x32_bf16 v[56:59], v[140:143], v[178:181], v[56:59]
	v_mfma_f32_16x16x32_bf16 v[44:47], v[132:135], v[198:201], v[44:47]
	v_mfma_f32_16x16x32_bf16 v[40:43], v[140:143], v[198:201], v[40:43]
	v_mfma_f32_16x16x32_bf16 v[28:31], v[132:135], v[206:209], v[28:31]
	v_mfma_f32_16x16x32_bf16 v[24:27], v[140:143], v[206:209], v[24:27]
	v_mfma_f32_16x16x32_bf16 v[12:15], v[132:135], v[214:217], v[12:15]
	v_mfma_f32_16x16x32_bf16 v[8:11], v[140:143], v[214:217], v[8:11]
	s_setprio 0
	s_setprio 1
	v_mfma_f32_16x16x32_bf16 v[52:55], v[144:147], v[174:177], 0
	v_mfma_f32_16x16x32_bf16 v[48:51], v[166:169], v[174:177], 0
	v_mfma_f32_16x16x32_bf16 v[36:39], v[144:147], v[194:197], 0
	v_mfma_f32_16x16x32_bf16 v[32:35], v[166:169], v[194:197], 0
	v_mfma_f32_16x16x32_bf16 v[20:23], v[144:147], v[202:205], 0
	v_mfma_f32_16x16x32_bf16 v[16:19], v[166:169], v[202:205], 0
	v_mfma_f32_16x16x32_bf16 v[4:7], v[144:147], v[210:213], 0
	v_mfma_f32_16x16x32_bf16 v[0:3], v[166:169], v[210:213], 0
	v_mfma_f32_16x16x32_bf16 v[52:55], v[148:151], v[178:181], v[52:55]
	v_mfma_f32_16x16x32_bf16 v[48:51], v[170:173], v[178:181], v[48:51]
	v_mfma_f32_16x16x32_bf16 v[36:39], v[148:151], v[198:201], v[36:39]
	v_mfma_f32_16x16x32_bf16 v[32:35], v[170:173], v[198:201], v[32:35]
	v_mfma_f32_16x16x32_bf16 v[20:23], v[148:151], v[206:209], v[20:23]
	v_mfma_f32_16x16x32_bf16 v[16:19], v[170:173], v[206:209], v[16:19]
	v_mfma_f32_16x16x32_bf16 v[4:7], v[148:151], v[214:217], v[4:7]
	v_mfma_f32_16x16x32_bf16 v[0:3], v[170:173], v[214:217], v[0:3]
	s_setprio 0
	s_barrier
	s_add_i32 s3, 0, 0x18000
	s_add_i32 s73, 0, 0x1c000
	ds_read_b128 v[128:131], v253
	ds_read_b128 v[132:135], v253 offset:1024
	ds_read_b128 v[136:139], v253 offset:2048
	ds_read_b128 v[140:143], v253 offset:3072
	ds_read_b128 v[144:147], v254
	ds_read_b128 v[148:151], v254 offset:1024
	ds_read_b128 v[166:169], v254 offset:2048
	ds_read_b128 v[170:173], v254 offset:3072
	s_add_u32 s38, s44, 0x158000
	s_addc_u32 s39, s45, 0
	s_mov_b32 m0, s51
	ds_read_b128 v[174:177], v190 offset:32768
	ds_read_b128 v[178:181], v190 offset:33792
	ds_read_b128 v[194:197], v190 offset:34816
	ds_read_b128 v[198:201], v190 offset:35840
	ds_read_b128 v[202:205], v190 offset:36864
	ds_read_b128 v[206:209], v190 offset:37888
	ds_read_b128 v[210:213], v190 offset:38912
	ds_read_b128 v[214:217], v190 offset:39936
	global_load_lds_dwordx4 v152, s[38:39]
	s_mov_b32 m0, s52
	s_nop 0
	global_load_lds_dwordx4 v156, s[38:39]
	s_waitcnt vmcnt(8)
	s_waitcnt lgkmcnt(0)
	s_setprio 1
	s_barrier
	v_mfma_f32_16x16x32_bf16 v[124:127], v[128:131], v[174:177], v[124:127]
	v_mfma_f32_16x16x32_bf16 v[120:123], v[136:139], v[174:177], v[120:123]
	v_mfma_f32_16x16x32_bf16 v[108:111], v[128:131], v[194:197], v[108:111]
	v_mfma_f32_16x16x32_bf16 v[104:107], v[136:139], v[194:197], v[104:107]
	v_mfma_f32_16x16x32_bf16 v[92:95], v[128:131], v[202:205], v[92:95]
	v_mfma_f32_16x16x32_bf16 v[88:91], v[136:139], v[202:205], v[88:91]
	v_mfma_f32_16x16x32_bf16 v[76:79], v[128:131], v[210:213], v[76:79]
	v_mfma_f32_16x16x32_bf16 v[72:75], v[136:139], v[210:213], v[72:75]
	v_mfma_f32_16x16x32_bf16 v[124:127], v[132:135], v[178:181], v[124:127]
	v_mfma_f32_16x16x32_bf16 v[120:123], v[140:143], v[178:181], v[120:123]
	v_mfma_f32_16x16x32_bf16 v[108:111], v[132:135], v[198:201], v[108:111]
	v_mfma_f32_16x16x32_bf16 v[104:107], v[140:143], v[198:201], v[104:107]
	v_mfma_f32_16x16x32_bf16 v[92:95], v[132:135], v[206:209], v[92:95]
	v_mfma_f32_16x16x32_bf16 v[88:91], v[140:143], v[206:209], v[88:91]
	v_mfma_f32_16x16x32_bf16 v[76:79], v[132:135], v[214:217], v[76:79]
	v_mfma_f32_16x16x32_bf16 v[72:75], v[140:143], v[214:217], v[72:75]
	s_setprio 0
	s_setprio 1
	v_mfma_f32_16x16x32_bf16 v[116:119], v[144:147], v[174:177], v[116:119]
	v_mfma_f32_16x16x32_bf16 v[112:115], v[166:169], v[174:177], v[112:115]
	v_mfma_f32_16x16x32_bf16 v[100:103], v[144:147], v[194:197], v[100:103]
	v_mfma_f32_16x16x32_bf16 v[96:99], v[166:169], v[194:197], v[96:99]
	v_mfma_f32_16x16x32_bf16 v[84:87], v[144:147], v[202:205], v[84:87]
	v_mfma_f32_16x16x32_bf16 v[80:83], v[166:169], v[202:205], v[80:83]
	v_mfma_f32_16x16x32_bf16 v[68:71], v[144:147], v[210:213], v[68:71]
	v_mfma_f32_16x16x32_bf16 v[64:67], v[166:169], v[210:213], v[64:67]
	v_mfma_f32_16x16x32_bf16 v[116:119], v[148:151], v[178:181], v[116:119]
	v_mfma_f32_16x16x32_bf16 v[112:115], v[170:173], v[178:181], v[112:115]
	v_mfma_f32_16x16x32_bf16 v[100:103], v[148:151], v[198:201], v[100:103]
	v_mfma_f32_16x16x32_bf16 v[96:99], v[170:173], v[198:201], v[96:99]
	v_mfma_f32_16x16x32_bf16 v[84:87], v[148:151], v[206:209], v[84:87]
	v_mfma_f32_16x16x32_bf16 v[80:83], v[170:173], v[206:209], v[80:83]
	v_mfma_f32_16x16x32_bf16 v[68:71], v[148:151], v[214:217], v[68:71]
	v_mfma_f32_16x16x32_bf16 v[64:67], v[170:173], v[214:217], v[64:67]
	s_setprio 0
	s_barrier
	s_add_i32 s3, s3, s33
	s_mov_b32 m0, s3
	ds_read_b128 v[174:177], v190 offset:49152
	ds_read_b128 v[178:181], v190 offset:50176
	ds_read_b128 v[194:197], v190 offset:51200
	ds_read_b128 v[198:201], v190 offset:52224
	ds_read_b128 v[202:205], v190 offset:53248
	ds_read_b128 v[206:209], v190 offset:54272
	ds_read_b128 v[210:213], v190 offset:55296
	ds_read_b128 v[214:217], v190 offset:56320
	global_load_lds_dwordx4 v154, s[98:99]
	s_add_i32 m0, s3, 0x2000
	s_add_u32 s38, s42, 0x158080
	s_addc_u32 s39, s43, 0
	s_add_i32 s3, s73, s33
	global_load_lds_dwordx4 v158, s[98:99]
	s_mov_b32 m0, s3
	s_nop 0
	global_load_lds_dwordx4 v154, s[38:39]
	s_add_i32 m0, s3, 0x2000
	s_nop 0
	global_load_lds_dwordx4 v158, s[38:39]
	s_mov_b32 m0, s56
	s_nop 0
	global_load_lds_dwordx4 v152, s[100:101]
	s_mov_b32 m0, s57
	s_nop 0
	global_load_lds_dwordx4 v156, s[100:101]
	s_waitcnt vmcnt(8)
	s_waitcnt lgkmcnt(0)
	s_setprio 1
	s_barrier
	v_mfma_f32_16x16x32_bf16 v[60:63], v[128:131], v[174:177], v[60:63]
	v_mfma_f32_16x16x32_bf16 v[56:59], v[136:139], v[174:177], v[56:59]
	v_mfma_f32_16x16x32_bf16 v[44:47], v[128:131], v[194:197], v[44:47]
	v_mfma_f32_16x16x32_bf16 v[40:43], v[136:139], v[194:197], v[40:43]
	v_mfma_f32_16x16x32_bf16 v[28:31], v[128:131], v[202:205], v[28:31]
	v_mfma_f32_16x16x32_bf16 v[24:27], v[136:139], v[202:205], v[24:27]
	v_mfma_f32_16x16x32_bf16 v[12:15], v[128:131], v[210:213], v[12:15]
	v_mfma_f32_16x16x32_bf16 v[8:11], v[136:139], v[210:213], v[8:11]
	v_mfma_f32_16x16x32_bf16 v[60:63], v[132:135], v[178:181], v[60:63]
	v_mfma_f32_16x16x32_bf16 v[56:59], v[140:143], v[178:181], v[56:59]
	v_mfma_f32_16x16x32_bf16 v[44:47], v[132:135], v[198:201], v[44:47]
	v_mfma_f32_16x16x32_bf16 v[40:43], v[140:143], v[198:201], v[40:43]
	v_mfma_f32_16x16x32_bf16 v[28:31], v[132:135], v[206:209], v[28:31]
	v_mfma_f32_16x16x32_bf16 v[24:27], v[140:143], v[206:209], v[24:27]
	v_mfma_f32_16x16x32_bf16 v[12:15], v[132:135], v[214:217], v[12:15]
	v_mfma_f32_16x16x32_bf16 v[8:11], v[140:143], v[214:217], v[8:11]
	s_setprio 0
	s_setprio 1
	v_mfma_f32_16x16x32_bf16 v[52:55], v[144:147], v[174:177], v[52:55]
	v_mfma_f32_16x16x32_bf16 v[48:51], v[166:169], v[174:177], v[48:51]
	v_mfma_f32_16x16x32_bf16 v[36:39], v[144:147], v[194:197], v[36:39]
	v_mfma_f32_16x16x32_bf16 v[32:35], v[166:169], v[194:197], v[32:35]
	v_mfma_f32_16x16x32_bf16 v[20:23], v[144:147], v[202:205], v[20:23]
	v_mfma_f32_16x16x32_bf16 v[16:19], v[166:169], v[202:205], v[16:19]
	v_mfma_f32_16x16x32_bf16 v[4:7], v[144:147], v[210:213], v[4:7]
	v_mfma_f32_16x16x32_bf16 v[0:3], v[166:169], v[210:213], v[0:3]
	v_mfma_f32_16x16x32_bf16 v[52:55], v[148:151], v[178:181], v[52:55]
	v_mfma_f32_16x16x32_bf16 v[48:51], v[170:173], v[178:181], v[48:51]
	v_mfma_f32_16x16x32_bf16 v[36:39], v[148:151], v[198:201], v[36:39]
	v_mfma_f32_16x16x32_bf16 v[32:35], v[170:173], v[198:201], v[32:35]
	v_mfma_f32_16x16x32_bf16 v[20:23], v[148:151], v[206:209], v[20:23]
	v_mfma_f32_16x16x32_bf16 v[16:19], v[170:173], v[206:209], v[16:19]
	v_mfma_f32_16x16x32_bf16 v[4:7], v[148:151], v[214:217], v[4:7]
	v_mfma_f32_16x16x32_bf16 v[0:3], v[170:173], v[214:217], v[0:3]
	s_setprio 0
	s_barrier
	s_add_i32 s1, s1, 2
	s_add_u32 s4, s4, 0x100
	s_addc_u32 s5, s5, 0
	s_cmpk_gt_u32 s1, 0x53
	s_mov_b64 s[38:39], s[40:41]
.LBB0_876:
	ds_read_b128 v[128:131], v188
	ds_read_b128 v[132:135], v188 offset:1024
	ds_read_b128 v[136:139], v188 offset:2048
	ds_read_b128 v[140:143], v188 offset:3072
	ds_read_b128 v[144:147], v189
	ds_read_b128 v[148:151], v189 offset:1024
	ds_read_b128 v[166:169], v189 offset:2048
	ds_read_b128 v[170:173], v189 offset:3072
	s_add_u32 s40, s38, 0x100
	s_addc_u32 s41, s39, 0
	s_cmpk_eq_i32 s1, 0x52
	s_cselect_b32 s45, s37, s41
	s_cselect_b32 s44, s36, s40
	s_cselect_b32 s43, s17, s5
	s_cselect_b32 s42, s16, s4
	s_add_i32 m0, s48, 0xc000
	ds_read_b128 v[174:177], v190
	ds_read_b128 v[178:181], v190 offset:1024
	ds_read_b128 v[194:197], v190 offset:2048
	ds_read_b128 v[198:201], v190 offset:3072
	ds_read_b128 v[202:205], v190 offset:4096
	ds_read_b128 v[206:209], v190 offset:5120
	ds_read_b128 v[210:213], v190 offset:6144
	ds_read_b128 v[214:217], v190 offset:7168
	global_load_lds_dwordx4 v160, s[38:39]
	s_add_i32 m0, s48, 0xe000
	s_nop 0
	global_load_lds_dwordx4 v162, s[38:39]
	s_waitcnt vmcnt(8)
	s_waitcnt lgkmcnt(0)
	s_setprio 1
	s_barrier
	v_mfma_f32_16x16x32_bf16 v[124:127], v[128:131], v[174:177], v[124:127]
	v_mfma_f32_16x16x32_bf16 v[120:123], v[136:139], v[174:177], v[120:123]
	v_mfma_f32_16x16x32_bf16 v[108:111], v[128:131], v[194:197], v[108:111]
	v_mfma_f32_16x16x32_bf16 v[104:107], v[136:139], v[194:197], v[104:107]
	v_mfma_f32_16x16x32_bf16 v[92:95], v[128:131], v[202:205], v[92:95]
	v_mfma_f32_16x16x32_bf16 v[88:91], v[136:139], v[202:205], v[88:91]
	v_mfma_f32_16x16x32_bf16 v[76:79], v[128:131], v[210:213], v[76:79]
	v_mfma_f32_16x16x32_bf16 v[72:75], v[136:139], v[210:213], v[72:75]
	v_mfma_f32_16x16x32_bf16 v[124:127], v[132:135], v[178:181], v[124:127]
	v_mfma_f32_16x16x32_bf16 v[120:123], v[140:143], v[178:181], v[120:123]
	v_mfma_f32_16x16x32_bf16 v[108:111], v[132:135], v[198:201], v[108:111]
	v_mfma_f32_16x16x32_bf16 v[104:107], v[140:143], v[198:201], v[104:107]
	v_mfma_f32_16x16x32_bf16 v[92:95], v[132:135], v[206:209], v[92:95]
	v_mfma_f32_16x16x32_bf16 v[88:91], v[140:143], v[206:209], v[88:91]
	v_mfma_f32_16x16x32_bf16 v[76:79], v[132:135], v[214:217], v[76:79]
	v_mfma_f32_16x16x32_bf16 v[72:75], v[140:143], v[214:217], v[72:75]
	s_setprio 0
	s_setprio 1
	v_mfma_f32_16x16x32_bf16 v[116:119], v[144:147], v[174:177], v[116:119]
	v_mfma_f32_16x16x32_bf16 v[112:115], v[166:169], v[174:177], v[112:115]
	v_mfma_f32_16x16x32_bf16 v[100:103], v[144:147], v[194:197], v[100:103]
	v_mfma_f32_16x16x32_bf16 v[96:99], v[166:169], v[194:197], v[96:99]
	v_mfma_f32_16x16x32_bf16 v[84:87], v[144:147], v[202:205], v[84:87]
	v_mfma_f32_16x16x32_bf16 v[80:83], v[166:169], v[202:205], v[80:83]
	v_mfma_f32_16x16x32_bf16 v[68:71], v[144:147], v[210:213], v[68:71]
	v_mfma_f32_16x16x32_bf16 v[64:67], v[166:169], v[210:213], v[64:67]
	v_mfma_f32_16x16x32_bf16 v[116:119], v[148:151], v[178:181], v[116:119]
	v_mfma_f32_16x16x32_bf16 v[112:115], v[170:173], v[178:181], v[112:115]
	v_mfma_f32_16x16x32_bf16 v[100:103], v[148:151], v[198:201], v[100:103]
	v_mfma_f32_16x16x32_bf16 v[96:99], v[170:173], v[198:201], v[96:99]
	v_mfma_f32_16x16x32_bf16 v[84:87], v[148:151], v[206:209], v[84:87]
	v_mfma_f32_16x16x32_bf16 v[80:83], v[170:173], v[206:209], v[80:83]
	v_mfma_f32_16x16x32_bf16 v[68:71], v[148:151], v[214:217], v[68:71]
	v_mfma_f32_16x16x32_bf16 v[64:67], v[170:173], v[214:217], v[64:67]
	s_setprio 0
	s_barrier
	s_add_i32 s3, s70, s33
	s_add_u32 s98, s42, s24
	s_addc_u32 s99, s43, s25
	s_mov_b32 m0, s3
	ds_read_b128 v[174:177], v190 offset:16384
	ds_read_b128 v[178:181], v190 offset:17408
	ds_read_b128 v[194:197], v190 offset:18432
	ds_read_b128 v[198:201], v190 offset:19456
	ds_read_b128 v[202:205], v190 offset:20480
	ds_read_b128 v[206:209], v190 offset:21504
	ds_read_b128 v[210:213], v190 offset:22528
	ds_read_b128 v[214:217], v190 offset:23552
	global_load_lds_dwordx4 v154, s[42:43]
	s_add_i32 m0, s3, 0x2000
	s_add_u32 s38, s42, 0x158000
	s_addc_u32 s39, s43, 0
	s_add_i32 s3, s71, s33
	global_load_lds_dwordx4 v158, s[42:43]
	s_mov_b32 m0, s3
	s_add_u32 s100, s44, s24
	s_addc_u32 s101, s45, s25
	global_load_lds_dwordx4 v154, s[38:39]
	s_add_i32 m0, s3, 0x2000
	s_nop 0
	global_load_lds_dwordx4 v158, s[38:39]
	s_mov_b32 m0, s48
	s_nop 0
	global_load_lds_dwordx4 v152, s[44:45]
	s_mov_b32 m0, s49
	s_nop 0
	global_load_lds_dwordx4 v156, s[44:45]
	s_waitcnt vmcnt(8)
	s_waitcnt lgkmcnt(0)
	s_setprio 1
	s_barrier
	v_mfma_f32_16x16x32_bf16 v[60:63], v[128:131], v[174:177], v[60:63]
	v_mfma_f32_16x16x32_bf16 v[56:59], v[136:139], v[174:177], v[56:59]
	v_mfma_f32_16x16x32_bf16 v[44:47], v[128:131], v[194:197], v[44:47]
	v_mfma_f32_16x16x32_bf16 v[40:43], v[136:139], v[194:197], v[40:43]
	v_mfma_f32_16x16x32_bf16 v[28:31], v[128:131], v[202:205], v[28:31]
	v_mfma_f32_16x16x32_bf16 v[24:27], v[136:139], v[202:205], v[24:27]
	v_mfma_f32_16x16x32_bf16 v[12:15], v[128:131], v[210:213], v[12:15]
	v_mfma_f32_16x16x32_bf16 v[8:11], v[136:139], v[210:213], v[8:11]
	v_mfma_f32_16x16x32_bf16 v[60:63], v[132:135], v[178:181], v[60:63]
	v_mfma_f32_16x16x32_bf16 v[56:59], v[140:143], v[178:181], v[56:59]
	v_mfma_f32_16x16x32_bf16 v[44:47], v[132:135], v[198:201], v[44:47]
	v_mfma_f32_16x16x32_bf16 v[40:43], v[140:143], v[198:201], v[40:43]
	v_mfma_f32_16x16x32_bf16 v[28:31], v[132:135], v[206:209], v[28:31]
	v_mfma_f32_16x16x32_bf16 v[24:27], v[140:143], v[206:209], v[24:27]
	v_mfma_f32_16x16x32_bf16 v[12:15], v[132:135], v[214:217], v[12:15]
	v_mfma_f32_16x16x32_bf16 v[8:11], v[140:143], v[214:217], v[8:11]
	s_setprio 0
	s_setprio 1
	v_mfma_f32_16x16x32_bf16 v[52:55], v[144:147], v[174:177], v[52:55]
	v_mfma_f32_16x16x32_bf16 v[48:51], v[166:169], v[174:177], v[48:51]
	v_mfma_f32_16x16x32_bf16 v[36:39], v[144:147], v[194:197], v[36:39]
	v_mfma_f32_16x16x32_bf16 v[32:35], v[166:169], v[194:197], v[32:35]
	v_mfma_f32_16x16x32_bf16 v[20:23], v[144:147], v[202:205], v[20:23]
	v_mfma_f32_16x16x32_bf16 v[16:19], v[166:169], v[202:205], v[16:19]
	v_mfma_f32_16x16x32_bf16 v[4:7], v[144:147], v[210:213], v[4:7]
	v_mfma_f32_16x16x32_bf16 v[0:3], v[166:169], v[210:213], v[0:3]
	v_mfma_f32_16x16x32_bf16 v[52:55], v[148:151], v[178:181], v[52:55]
	v_mfma_f32_16x16x32_bf16 v[48:51], v[170:173], v[178:181], v[48:51]
	v_mfma_f32_16x16x32_bf16 v[36:39], v[148:151], v[198:201], v[36:39]
	v_mfma_f32_16x16x32_bf16 v[32:35], v[170:173], v[198:201], v[32:35]
	v_mfma_f32_16x16x32_bf16 v[20:23], v[148:151], v[206:209], v[20:23]
	v_mfma_f32_16x16x32_bf16 v[16:19], v[170:173], v[206:209], v[16:19]
	v_mfma_f32_16x16x32_bf16 v[4:7], v[148:151], v[214:217], v[4:7]
	v_mfma_f32_16x16x32_bf16 v[0:3], v[170:173], v[214:217], v[0:3]
	s_setprio 0
	s_barrier
	s_add_i32 s3, 0, 0x18000
	s_add_i32 s73, 0, 0x1c000
	ds_read_b128 v[128:131], v253
	ds_read_b128 v[132:135], v253 offset:1024
	ds_read_b128 v[136:139], v253 offset:2048
	ds_read_b128 v[140:143], v253 offset:3072
	ds_read_b128 v[144:147], v254
	ds_read_b128 v[148:151], v254 offset:1024
	ds_read_b128 v[166:169], v254 offset:2048
	ds_read_b128 v[170:173], v254 offset:3072
	s_add_u32 s38, s44, 0x158000
	s_addc_u32 s39, s45, 0
	s_mov_b32 m0, s51
	ds_read_b128 v[174:177], v190 offset:32768
	ds_read_b128 v[178:181], v190 offset:33792
	ds_read_b128 v[194:197], v190 offset:34816
	ds_read_b128 v[198:201], v190 offset:35840
	ds_read_b128 v[202:205], v190 offset:36864
	ds_read_b128 v[206:209], v190 offset:37888
	ds_read_b128 v[210:213], v190 offset:38912
	ds_read_b128 v[214:217], v190 offset:39936
	global_load_lds_dwordx4 v152, s[38:39]
	s_mov_b32 m0, s52
	s_nop 0
	global_load_lds_dwordx4 v156, s[38:39]
	s_waitcnt vmcnt(8)
	s_waitcnt lgkmcnt(0)
	s_setprio 1
	s_barrier
	v_mfma_f32_16x16x32_bf16 v[124:127], v[128:131], v[174:177], v[124:127]
	v_mfma_f32_16x16x32_bf16 v[120:123], v[136:139], v[174:177], v[120:123]
	v_mfma_f32_16x16x32_bf16 v[108:111], v[128:131], v[194:197], v[108:111]
	v_mfma_f32_16x16x32_bf16 v[104:107], v[136:139], v[194:197], v[104:107]
	v_mfma_f32_16x16x32_bf16 v[92:95], v[128:131], v[202:205], v[92:95]
	v_mfma_f32_16x16x32_bf16 v[88:91], v[136:139], v[202:205], v[88:91]
	v_mfma_f32_16x16x32_bf16 v[76:79], v[128:131], v[210:213], v[76:79]
	v_mfma_f32_16x16x32_bf16 v[72:75], v[136:139], v[210:213], v[72:75]
	v_mfma_f32_16x16x32_bf16 v[124:127], v[132:135], v[178:181], v[124:127]
	v_mfma_f32_16x16x32_bf16 v[120:123], v[140:143], v[178:181], v[120:123]
	v_mfma_f32_16x16x32_bf16 v[108:111], v[132:135], v[198:201], v[108:111]
	v_mfma_f32_16x16x32_bf16 v[104:107], v[140:143], v[198:201], v[104:107]
	v_mfma_f32_16x16x32_bf16 v[92:95], v[132:135], v[206:209], v[92:95]
	v_mfma_f32_16x16x32_bf16 v[88:91], v[140:143], v[206:209], v[88:91]
	v_mfma_f32_16x16x32_bf16 v[76:79], v[132:135], v[214:217], v[76:79]
	v_mfma_f32_16x16x32_bf16 v[72:75], v[140:143], v[214:217], v[72:75]
	s_setprio 0
	s_setprio 1
	v_mfma_f32_16x16x32_bf16 v[116:119], v[144:147], v[174:177], v[116:119]
	v_mfma_f32_16x16x32_bf16 v[112:115], v[166:169], v[174:177], v[112:115]
	v_mfma_f32_16x16x32_bf16 v[100:103], v[144:147], v[194:197], v[100:103]
	v_mfma_f32_16x16x32_bf16 v[96:99], v[166:169], v[194:197], v[96:99]
	v_mfma_f32_16x16x32_bf16 v[84:87], v[144:147], v[202:205], v[84:87]
	v_mfma_f32_16x16x32_bf16 v[80:83], v[166:169], v[202:205], v[80:83]
	v_mfma_f32_16x16x32_bf16 v[68:71], v[144:147], v[210:213], v[68:71]
	v_mfma_f32_16x16x32_bf16 v[64:67], v[166:169], v[210:213], v[64:67]
	v_mfma_f32_16x16x32_bf16 v[116:119], v[148:151], v[178:181], v[116:119]
	v_mfma_f32_16x16x32_bf16 v[112:115], v[170:173], v[178:181], v[112:115]
	v_mfma_f32_16x16x32_bf16 v[100:103], v[148:151], v[198:201], v[100:103]
	v_mfma_f32_16x16x32_bf16 v[96:99], v[170:173], v[198:201], v[96:99]
	v_mfma_f32_16x16x32_bf16 v[84:87], v[148:151], v[206:209], v[84:87]
	v_mfma_f32_16x16x32_bf16 v[80:83], v[170:173], v[206:209], v[80:83]
	v_mfma_f32_16x16x32_bf16 v[68:71], v[148:151], v[214:217], v[68:71]
	v_mfma_f32_16x16x32_bf16 v[64:67], v[170:173], v[214:217], v[64:67]
	s_setprio 0
	s_barrier
	s_add_i32 s3, s3, s33
	s_mov_b32 m0, s3
	ds_read_b128 v[174:177], v190 offset:49152
	ds_read_b128 v[178:181], v190 offset:50176
	ds_read_b128 v[194:197], v190 offset:51200
	ds_read_b128 v[198:201], v190 offset:52224
	ds_read_b128 v[202:205], v190 offset:53248
	ds_read_b128 v[206:209], v190 offset:54272
	ds_read_b128 v[210:213], v190 offset:55296
	ds_read_b128 v[214:217], v190 offset:56320
	global_load_lds_dwordx4 v154, s[98:99]
	s_add_i32 m0, s3, 0x2000
	s_add_u32 s38, s42, 0x158080
	s_addc_u32 s39, s43, 0
	s_add_i32 s3, s73, s33
	global_load_lds_dwordx4 v158, s[98:99]
	s_mov_b32 m0, s3
	s_nop 0
	global_load_lds_dwordx4 v154, s[38:39]
	s_add_i32 m0, s3, 0x2000
	s_nop 0
	global_load_lds_dwordx4 v158, s[38:39]
	s_mov_b32 m0, s56
	s_nop 0
	global_load_lds_dwordx4 v152, s[100:101]
	s_mov_b32 m0, s57
	s_nop 0
	global_load_lds_dwordx4 v156, s[100:101]
	s_waitcnt vmcnt(8)
	s_waitcnt lgkmcnt(0)
	s_setprio 1
	s_barrier
	v_mfma_f32_16x16x32_bf16 v[60:63], v[128:131], v[174:177], v[60:63]
	v_mfma_f32_16x16x32_bf16 v[56:59], v[136:139], v[174:177], v[56:59]
	v_mfma_f32_16x16x32_bf16 v[44:47], v[128:131], v[194:197], v[44:47]
	v_mfma_f32_16x16x32_bf16 v[40:43], v[136:139], v[194:197], v[40:43]
	v_mfma_f32_16x16x32_bf16 v[28:31], v[128:131], v[202:205], v[28:31]
	v_mfma_f32_16x16x32_bf16 v[24:27], v[136:139], v[202:205], v[24:27]
	v_mfma_f32_16x16x32_bf16 v[12:15], v[128:131], v[210:213], v[12:15]
	v_mfma_f32_16x16x32_bf16 v[8:11], v[136:139], v[210:213], v[8:11]
	v_mfma_f32_16x16x32_bf16 v[60:63], v[132:135], v[178:181], v[60:63]
	v_mfma_f32_16x16x32_bf16 v[56:59], v[140:143], v[178:181], v[56:59]
	v_mfma_f32_16x16x32_bf16 v[44:47], v[132:135], v[198:201], v[44:47]
	v_mfma_f32_16x16x32_bf16 v[40:43], v[140:143], v[198:201], v[40:43]
	v_mfma_f32_16x16x32_bf16 v[28:31], v[132:135], v[206:209], v[28:31]
	v_mfma_f32_16x16x32_bf16 v[24:27], v[140:143], v[206:209], v[24:27]
	v_mfma_f32_16x16x32_bf16 v[12:15], v[132:135], v[214:217], v[12:15]
	v_mfma_f32_16x16x32_bf16 v[8:11], v[140:143], v[214:217], v[8:11]
	s_setprio 0
	s_setprio 1
	v_mfma_f32_16x16x32_bf16 v[52:55], v[144:147], v[174:177], v[52:55]
	v_mfma_f32_16x16x32_bf16 v[48:51], v[166:169], v[174:177], v[48:51]
	v_mfma_f32_16x16x32_bf16 v[36:39], v[144:147], v[194:197], v[36:39]
	v_mfma_f32_16x16x32_bf16 v[32:35], v[166:169], v[194:197], v[32:35]
	v_mfma_f32_16x16x32_bf16 v[20:23], v[144:147], v[202:205], v[20:23]
	v_mfma_f32_16x16x32_bf16 v[16:19], v[166:169], v[202:205], v[16:19]
	v_mfma_f32_16x16x32_bf16 v[4:7], v[144:147], v[210:213], v[4:7]
	v_mfma_f32_16x16x32_bf16 v[0:3], v[166:169], v[210:213], v[0:3]
	v_mfma_f32_16x16x32_bf16 v[52:55], v[148:151], v[178:181], v[52:55]
	v_mfma_f32_16x16x32_bf16 v[48:51], v[170:173], v[178:181], v[48:51]
	v_mfma_f32_16x16x32_bf16 v[36:39], v[148:151], v[198:201], v[36:39]
	v_mfma_f32_16x16x32_bf16 v[32:35], v[170:173], v[198:201], v[32:35]
	v_mfma_f32_16x16x32_bf16 v[20:23], v[148:151], v[206:209], v[20:23]
	v_mfma_f32_16x16x32_bf16 v[16:19], v[170:173], v[206:209], v[16:19]
	v_mfma_f32_16x16x32_bf16 v[4:7], v[148:151], v[214:217], v[4:7]
	v_mfma_f32_16x16x32_bf16 v[0:3], v[170:173], v[214:217], v[0:3]
	s_setprio 0
	s_barrier
	s_add_i32 s1, s1, 2
	s_add_u32 s4, s4, 0x100
	s_addc_u32 s5, s5, 0
	s_cmpk_gt_u32 s1, 0x53
	s_mov_b64 s[38:39], s[40:41]
	s_cbranch_scc0 .LBB0_876
	s_and_b64 vcc, exec, s[26:27]
	s_cbranch_vccz .LBB0_879
	s_barrier
